# GEMM K-loops: the remaining 48 LDS-DMA address adds removed (re-used addresses captured as scalar base pairs); no 64-bit VALU left in the big K-loops
# baseline (speedup 1.0000x reference)
.Lz_skip_0:
	s_waitcnt vmcnt(8)
	s_waitcnt lgkmcnt(0)
	s_barrier
	s_waitcnt lgkmcnt(0)
	v_mfma_f32_16x16x32_bf16 v[124:127], v[144:147], v[186:189], v[124:127]
	v_mfma_f32_16x16x32_bf16 v[116:119], v[162:165], v[186:189], v[116:119]
	v_mfma_f32_16x16x32_bf16 v[108:111], v[144:147], v[194:197], v[108:111]
	v_mfma_f32_16x16x32_bf16 v[100:103], v[162:165], v[194:197], v[100:103]
	v_mfma_f32_16x16x32_bf16 v[92:95], v[144:147], v[202:205], v[92:95]
	v_mfma_f32_16x16x32_bf16 v[84:87], v[162:165], v[202:205], v[84:87]
	v_mfma_f32_16x16x32_bf16 v[76:79], v[144:147], v[222:225], v[76:79]
	v_mfma_f32_16x16x32_bf16 v[68:71], v[162:165], v[222:225], v[68:71]
	v_mfma_f32_16x16x32_bf16 v[124:127], v[158:161], v[190:193], v[124:127]
	v_mfma_f32_16x16x32_bf16 v[116:119], v[166:169], v[190:193], v[116:119]
	v_mfma_f32_16x16x32_bf16 v[108:111], v[158:161], v[198:201], v[108:111]
	v_mfma_f32_16x16x32_bf16 v[100:103], v[166:169], v[198:201], v[100:103]
	v_mfma_f32_16x16x32_bf16 v[92:95], v[158:161], v[218:221], v[92:95]
	v_mfma_f32_16x16x32_bf16 v[84:87], v[166:169], v[218:221], v[84:87]
	v_mfma_f32_16x16x32_bf16 v[76:79], v[158:161], v[226:229], v[76:79]
	v_mfma_f32_16x16x32_bf16 v[68:71], v[166:169], v[226:229], v[68:71]
	v_mfma_f32_16x16x32_bf16 v[120:123], v[170:173], v[186:189], v[120:123]
	v_mfma_f32_16x16x32_bf16 v[112:115], v[178:181], v[186:189], v[112:115]
	v_mfma_f32_16x16x32_bf16 v[104:107], v[170:173], v[194:197], v[104:107]
	v_mfma_f32_16x16x32_bf16 v[96:99], v[178:181], v[194:197], v[96:99]
	v_mfma_f32_16x16x32_bf16 v[88:91], v[170:173], v[202:205], v[88:91]
	v_mfma_f32_16x16x32_bf16 v[80:83], v[178:181], v[202:205], v[80:83]
	v_mfma_f32_16x16x32_bf16 v[72:75], v[170:173], v[222:225], v[72:75]
	v_mfma_f32_16x16x32_bf16 v[64:67], v[178:181], v[222:225], v[64:67]
	v_mfma_f32_16x16x32_bf16 v[120:123], v[174:177], v[190:193], v[120:123]
	v_mfma_f32_16x16x32_bf16 v[112:115], v[182:185], v[190:193], v[112:115]
	v_mfma_f32_16x16x32_bf16 v[104:107], v[174:177], v[198:201], v[104:107]
	v_mfma_f32_16x16x32_bf16 v[96:99], v[182:185], v[198:201], v[96:99]
	v_mfma_f32_16x16x32_bf16 v[88:91], v[174:177], v[218:221], v[88:91]
	v_mfma_f32_16x16x32_bf16 v[80:83], v[182:185], v[218:221], v[80:83]
	v_mfma_f32_16x16x32_bf16 v[72:75], v[174:177], v[226:229], v[72:75]
	v_mfma_f32_16x16x32_bf16 v[64:67], v[182:185], v[226:229], v[64:67]
	s_barrier
	s_add_i32 s55, s55, s37
	s_add_u32 s98, s26, s28
	s_addc_u32 s99, s27, s29
	s_mov_b32 m0, s55
	ds_read_b128 v[186:189], v143 offset:16384
	ds_read_b128 v[190:193], v143 offset:17408
	ds_read_b128 v[194:197], v143 offset:18432
	ds_read_b128 v[198:201], v143 offset:19456
	ds_read_b128 v[202:205], v143 offset:20480
	ds_read_b128 v[218:221], v143 offset:21504
	ds_read_b128 v[222:225], v143 offset:22528
	ds_read_b128 v[226:229], v143 offset:23552
	global_load_lds_dwordx4 v148, s[26:27]
	s_add_i32 m0, s55, 0x2000
	s_add_u32 s56, s26, 0x40000
	s_addc_u32 s57, s27, 0
	s_add_i32 s55, s58, s37
	global_load_lds_dwordx4 v128, s[26:27]
	s_mov_b32 m0, s55
	s_add_u32 s100, s30, s28
	s_addc_u32 s101, s31, s29
	global_load_lds_dwordx4 v148, s[56:57]
	s_add_i32 m0, s55, 0x2000
	s_nop 0
	global_load_lds_dwordx4 v128, s[56:57]
	s_mov_b32 m0, s38
	s_nop 0
	global_load_lds_dwordx4 v132, s[30:31]
	s_mov_b32 m0, s39
	s_nop 0
	global_load_lds_dwordx4 v130, s[30:31]
	s_waitcnt vmcnt(8)
	s_waitcnt lgkmcnt(0)
	s_barrier
	s_waitcnt lgkmcnt(0)
	v_mfma_f32_16x16x32_bf16 v[60:63], v[144:147], v[186:189], v[60:63]
	v_mfma_f32_16x16x32_bf16 v[52:55], v[162:165], v[186:189], v[52:55]
	v_mfma_f32_16x16x32_bf16 v[44:47], v[144:147], v[194:197], v[44:47]
	v_mfma_f32_16x16x32_bf16 v[36:39], v[162:165], v[194:197], v[36:39]
	v_mfma_f32_16x16x32_bf16 v[28:31], v[144:147], v[202:205], v[28:31]
	v_mfma_f32_16x16x32_bf16 v[20:23], v[162:165], v[202:205], v[20:23]
	v_mfma_f32_16x16x32_bf16 v[12:15], v[144:147], v[222:225], v[12:15]
	v_mfma_f32_16x16x32_bf16 v[4:7], v[162:165], v[222:225], v[4:7]
	v_mfma_f32_16x16x32_bf16 v[60:63], v[158:161], v[190:193], v[60:63]
	v_mfma_f32_16x16x32_bf16 v[52:55], v[166:169], v[190:193], v[52:55]
	v_mfma_f32_16x16x32_bf16 v[44:47], v[158:161], v[198:201], v[44:47]
	v_mfma_f32_16x16x32_bf16 v[36:39], v[166:169], v[198:201], v[36:39]
	v_mfma_f32_16x16x32_bf16 v[28:31], v[158:161], v[218:221], v[28:31]
	v_mfma_f32_16x16x32_bf16 v[20:23], v[166:169], v[218:221], v[20:23]
	v_mfma_f32_16x16x32_bf16 v[12:15], v[158:161], v[226:229], v[12:15]
	v_mfma_f32_16x16x32_bf16 v[4:7], v[166:169], v[226:229], v[4:7]
	v_mfma_f32_16x16x32_bf16 v[56:59], v[170:173], v[186:189], v[56:59]
	v_mfma_f32_16x16x32_bf16 v[48:51], v[178:181], v[186:189], v[48:51]
	v_mfma_f32_16x16x32_bf16 v[40:43], v[170:173], v[194:197], v[40:43]
	v_mfma_f32_16x16x32_bf16 v[32:35], v[178:181], v[194:197], v[32:35]
	v_mfma_f32_16x16x32_bf16 v[24:27], v[170:173], v[202:205], v[24:27]
	v_mfma_f32_16x16x32_bf16 v[16:19], v[178:181], v[202:205], v[16:19]
	v_mfma_f32_16x16x32_bf16 v[8:11], v[170:173], v[222:225], v[8:11]
	v_mfma_f32_16x16x32_bf16 v[0:3], v[178:181], v[222:225], v[0:3]
	v_mfma_f32_16x16x32_bf16 v[56:59], v[174:177], v[190:193], v[56:59]
	v_mfma_f32_16x16x32_bf16 v[48:51], v[182:185], v[190:193], v[48:51]
	v_mfma_f32_16x16x32_bf16 v[40:43], v[174:177], v[198:201], v[40:43]
	v_mfma_f32_16x16x32_bf16 v[32:35], v[182:185], v[198:201], v[32:35]
	v_mfma_f32_16x16x32_bf16 v[24:27], v[174:177], v[218:221], v[24:27]
	v_mfma_f32_16x16x32_bf16 v[16:19], v[182:185], v[218:221], v[16:19]
	v_mfma_f32_16x16x32_bf16 v[8:11], v[174:177], v[226:229], v[8:11]
	v_mfma_f32_16x16x32_bf16 v[0:3], v[182:185], v[226:229], v[0:3]
	s_barrier
	s_add_i32 s55, 0, 0x18000
	v_add_u32_e32 v140, s55, v141
	s_add_i32 s56, 0, 0x1c000
	ds_read_b128 v[144:147], v140
	ds_read_b128 v[158:161], v140 offset:1024
	ds_read_b128 v[162:165], v140 offset:2048
	ds_read_b128 v[166:169], v140 offset:3072
	v_add_u32_e32 v140, s56, v141
	ds_read_b128 v[170:173], v140
	ds_read_b128 v[174:177], v140 offset:1024
	ds_read_b128 v[178:181], v140 offset:2048
	ds_read_b128 v[182:185], v140 offset:3072
	s_add_u32 s30, s30, 0x40000
	s_addc_u32 s31, s31, 0
	s_mov_b32 m0, s40
	ds_read_b128 v[186:189], v143 offset:32768
	ds_read_b128 v[190:193], v143 offset:33792
	ds_read_b128 v[194:197], v143 offset:34816
	ds_read_b128 v[198:201], v143 offset:35840
	ds_read_b128 v[202:205], v143 offset:36864
	ds_read_b128 v[218:221], v143 offset:37888
	ds_read_b128 v[222:225], v143 offset:38912
	ds_read_b128 v[226:229], v143 offset:39936
	global_load_lds_dwordx4 v132, s[30:31]
	s_mov_b32 m0, s41
	s_nop 0
	global_load_lds_dwordx4 v130, s[30:31]
	s_waitcnt vmcnt(8)
	s_waitcnt lgkmcnt(0)
	s_barrier
	s_waitcnt lgkmcnt(0)
	v_mfma_f32_16x16x32_bf16 v[124:127], v[144:147], v[186:189], v[124:127]
	v_mfma_f32_16x16x32_bf16 v[116:119], v[162:165], v[186:189], v[116:119]
	v_mfma_f32_16x16x32_bf16 v[108:111], v[144:147], v[194:197], v[108:111]
	v_mfma_f32_16x16x32_bf16 v[100:103], v[162:165], v[194:197], v[100:103]
	v_mfma_f32_16x16x32_bf16 v[92:95], v[144:147], v[202:205], v[92:95]
	v_mfma_f32_16x16x32_bf16 v[84:87], v[162:165], v[202:205], v[84:87]
	v_mfma_f32_16x16x32_bf16 v[76:79], v[144:147], v[222:225], v[76:79]
	v_mfma_f32_16x16x32_bf16 v[68:71], v[162:165], v[222:225], v[68:71]
	v_mfma_f32_16x16x32_bf16 v[124:127], v[158:161], v[190:193], v[124:127]
	v_mfma_f32_16x16x32_bf16 v[116:119], v[166:169], v[190:193], v[116:119]
	v_mfma_f32_16x16x32_bf16 v[108:111], v[158:161], v[198:201], v[108:111]
	v_mfma_f32_16x16x32_bf16 v[100:103], v[166:169], v[198:201], v[100:103]
	v_mfma_f32_16x16x32_bf16 v[92:95], v[158:161], v[218:221], v[92:95]
	v_mfma_f32_16x16x32_bf16 v[84:87], v[166:169], v[218:221], v[84:87]
	v_mfma_f32_16x16x32_bf16 v[76:79], v[158:161], v[226:229], v[76:79]
	v_mfma_f32_16x16x32_bf16 v[68:71], v[166:169], v[226:229], v[68:71]
	v_mfma_f32_16x16x32_bf16 v[120:123], v[170:173], v[186:189], v[120:123]
	v_mfma_f32_16x16x32_bf16 v[112:115], v[178:181], v[186:189], v[112:115]
	v_mfma_f32_16x16x32_bf16 v[104:107], v[170:173], v[194:197], v[104:107]
	v_mfma_f32_16x16x32_bf16 v[96:99], v[178:181], v[194:197], v[96:99]
	v_mfma_f32_16x16x32_bf16 v[88:91], v[170:173], v[202:205], v[88:91]
	v_mfma_f32_16x16x32_bf16 v[80:83], v[178:181], v[202:205], v[80:83]
	v_mfma_f32_16x16x32_bf16 v[72:75], v[170:173], v[222:225], v[72:75]
	v_mfma_f32_16x16x32_bf16 v[64:67], v[178:181], v[222:225], v[64:67]
	v_mfma_f32_16x16x32_bf16 v[120:123], v[174:177], v[190:193], v[120:123]
	v_mfma_f32_16x16x32_bf16 v[112:115], v[182:185], v[190:193], v[112:115]
	v_mfma_f32_16x16x32_bf16 v[104:107], v[174:177], v[198:201], v[104:107]
	v_mfma_f32_16x16x32_bf16 v[96:99], v[182:185], v[198:201], v[96:99]
	v_mfma_f32_16x16x32_bf16 v[88:91], v[174:177], v[218:221], v[88:91]
	v_mfma_f32_16x16x32_bf16 v[80:83], v[182:185], v[218:221], v[80:83]
	v_mfma_f32_16x16x32_bf16 v[72:75], v[174:177], v[226:229], v[72:75]
	v_mfma_f32_16x16x32_bf16 v[64:67], v[182:185], v[226:229], v[64:67]
	s_barrier
	s_add_i32 s30, s55, s37
	s_mov_b32 m0, s30
	ds_read_b128 v[186:189], v143 offset:49152
	ds_read_b128 v[190:193], v143 offset:50176
	ds_read_b128 v[194:197], v143 offset:51200
	ds_read_b128 v[198:201], v143 offset:52224
	ds_read_b128 v[202:205], v143 offset:53248
	ds_read_b128 v[218:221], v143 offset:54272
	ds_read_b128 v[222:225], v143 offset:55296
	ds_read_b128 v[226:229], v143 offset:56320
	global_load_lds_dwordx4 v148, s[98:99]
	s_add_i32 m0, s30, 0x2000
	s_add_u32 s26, s26, 0x40080
	s_addc_u32 s27, s27, 0
	s_add_i32 s30, s56, s37
	global_load_lds_dwordx4 v128, s[98:99]
	s_mov_b32 m0, s30
	s_nop 0
	global_load_lds_dwordx4 v148, s[26:27]
	s_add_i32 m0, s30, 0x2000
	s_nop 0
	global_load_lds_dwordx4 v128, s[26:27]
	s_mov_b32 m0, s46
	s_nop 0
	global_load_lds_dwordx4 v132, s[100:101]
	s_mov_b32 m0, s47
	s_nop 0
	global_load_lds_dwordx4 v130, s[100:101]
	s_waitcnt vmcnt(8)
	s_waitcnt lgkmcnt(0)
	s_barrier
	s_waitcnt lgkmcnt(0)
	v_mfma_f32_16x16x32_bf16 v[60:63], v[144:147], v[186:189], v[60:63]
	v_mfma_f32_16x16x32_bf16 v[52:55], v[162:165], v[186:189], v[52:55]
	v_mfma_f32_16x16x32_bf16 v[44:47], v[144:147], v[194:197], v[44:47]
	v_mfma_f32_16x16x32_bf16 v[36:39], v[162:165], v[194:197], v[36:39]
	v_mfma_f32_16x16x32_bf16 v[28:31], v[144:147], v[202:205], v[28:31]
	v_mfma_f32_16x16x32_bf16 v[20:23], v[162:165], v[202:205], v[20:23]
	v_mfma_f32_16x16x32_bf16 v[12:15], v[144:147], v[222:225], v[12:15]
	v_mfma_f32_16x16x32_bf16 v[4:7], v[162:165], v[222:225], v[4:7]
	v_mfma_f32_16x16x32_bf16 v[60:63], v[158:161], v[190:193], v[60:63]
	v_mfma_f32_16x16x32_bf16 v[52:55], v[166:169], v[190:193], v[52:55]
	v_mfma_f32_16x16x32_bf16 v[44:47], v[158:161], v[198:201], v[44:47]
	v_mfma_f32_16x16x32_bf16 v[36:39], v[166:169], v[198:201], v[36:39]
	v_mfma_f32_16x16x32_bf16 v[28:31], v[158:161], v[218:221], v[28:31]
	v_mfma_f32_16x16x32_bf16 v[20:23], v[166:169], v[218:221], v[20:23]
	v_mfma_f32_16x16x32_bf16 v[12:15], v[158:161], v[226:229], v[12:15]
	v_mfma_f32_16x16x32_bf16 v[4:7], v[166:169], v[226:229], v[4:7]
	v_mfma_f32_16x16x32_bf16 v[56:59], v[170:173], v[186:189], v[56:59]
	v_mfma_f32_16x16x32_bf16 v[48:51], v[178:181], v[186:189], v[48:51]
	v_mfma_f32_16x16x32_bf16 v[40:43], v[170:173], v[194:197], v[40:43]
	v_mfma_f32_16x16x32_bf16 v[32:35], v[178:181], v[194:197], v[32:35]
	v_mfma_f32_16x16x32_bf16 v[24:27], v[170:173], v[202:205], v[24:27]
	v_mfma_f32_16x16x32_bf16 v[16:19], v[178:181], v[202:205], v[16:19]
	v_mfma_f32_16x16x32_bf16 v[8:11], v[170:173], v[222:225], v[8:11]
	v_mfma_f32_16x16x32_bf16 v[0:3], v[178:181], v[222:225], v[0:3]
	v_mfma_f32_16x16x32_bf16 v[56:59], v[174:177], v[190:193], v[56:59]
	v_mfma_f32_16x16x32_bf16 v[48:51], v[182:185], v[190:193], v[48:51]
	v_mfma_f32_16x16x32_bf16 v[40:43], v[174:177], v[198:201], v[40:43]
	v_mfma_f32_16x16x32_bf16 v[32:35], v[182:185], v[198:201], v[32:35]
	v_mfma_f32_16x16x32_bf16 v[24:27], v[174:177], v[218:221], v[24:27]
	v_mfma_f32_16x16x32_bf16 v[16:19], v[182:185], v[218:221], v[16:19]
	v_mfma_f32_16x16x32_bf16 v[8:11], v[174:177], v[226:229], v[8:11]
	v_mfma_f32_16x16x32_bf16 v[0:3], v[182:185], v[226:229], v[0:3]
	s_barrier
	s_add_i32 s54, s54, 2
	s_add_u32 s0, s0, 0x100
	s_addc_u32 s1, s1, 0
	s_add_u32 s52, s52, 0x100
	s_addc_u32 s53, s53, 0
	s_cmp_gt_u32 s54, 13
	s_cbranch_scc0 .LBB0_253
	s_and_b64 vcc, exec, s[8:9]
	s_cbranch_vccz .LBB0_256
	s_barrier

.Lz_skip_1:
	s_waitcnt vmcnt(8)
	s_waitcnt lgkmcnt(0)
	s_barrier
	s_waitcnt lgkmcnt(0)
	v_mfma_f32_16x16x32_bf16 v[124:127], v[128:131], v[186:189], v[124:127]
	v_mfma_f32_16x16x32_bf16 v[120:123], v[158:161], v[186:189], v[120:123]
	v_mfma_f32_16x16x32_bf16 v[108:111], v[128:131], v[194:197], v[108:111]
	v_mfma_f32_16x16x32_bf16 v[104:107], v[158:161], v[194:197], v[104:107]
	v_mfma_f32_16x16x32_bf16 v[92:95], v[128:131], v[202:205], v[92:95]
	v_mfma_f32_16x16x32_bf16 v[88:91], v[158:161], v[202:205], v[88:91]
	v_mfma_f32_16x16x32_bf16 v[76:79], v[128:131], v[222:225], v[76:79]
	v_mfma_f32_16x16x32_bf16 v[72:75], v[158:161], v[222:225], v[72:75]
	v_mfma_f32_16x16x32_bf16 v[124:127], v[132:135], v[190:193], v[124:127]
	v_mfma_f32_16x16x32_bf16 v[120:123], v[162:165], v[190:193], v[120:123]
	v_mfma_f32_16x16x32_bf16 v[108:111], v[132:135], v[198:201], v[108:111]
	v_mfma_f32_16x16x32_bf16 v[104:107], v[162:165], v[198:201], v[104:107]
	v_mfma_f32_16x16x32_bf16 v[92:95], v[132:135], v[218:221], v[92:95]
	v_mfma_f32_16x16x32_bf16 v[88:91], v[162:165], v[218:221], v[88:91]
	v_mfma_f32_16x16x32_bf16 v[76:79], v[132:135], v[226:229], v[76:79]
	v_mfma_f32_16x16x32_bf16 v[72:75], v[162:165], v[226:229], v[72:75]
	v_mfma_f32_16x16x32_bf16 v[116:119], v[170:173], v[186:189], v[116:119]
	v_mfma_f32_16x16x32_bf16 v[112:115], v[178:181], v[186:189], v[112:115]
	v_mfma_f32_16x16x32_bf16 v[100:103], v[170:173], v[194:197], v[100:103]
	v_mfma_f32_16x16x32_bf16 v[96:99], v[178:181], v[194:197], v[96:99]
	v_mfma_f32_16x16x32_bf16 v[84:87], v[170:173], v[202:205], v[84:87]
	v_mfma_f32_16x16x32_bf16 v[80:83], v[178:181], v[202:205], v[80:83]
	v_mfma_f32_16x16x32_bf16 v[68:71], v[170:173], v[222:225], v[68:71]
	v_mfma_f32_16x16x32_bf16 v[64:67], v[178:181], v[222:225], v[64:67]
	v_mfma_f32_16x16x32_bf16 v[116:119], v[174:177], v[190:193], v[116:119]
	v_mfma_f32_16x16x32_bf16 v[112:115], v[182:185], v[190:193], v[112:115]
	v_mfma_f32_16x16x32_bf16 v[100:103], v[174:177], v[198:201], v[100:103]
	v_mfma_f32_16x16x32_bf16 v[96:99], v[182:185], v[198:201], v[96:99]
	v_mfma_f32_16x16x32_bf16 v[84:87], v[174:177], v[218:221], v[84:87]
	v_mfma_f32_16x16x32_bf16 v[80:83], v[182:185], v[218:221], v[80:83]
	v_mfma_f32_16x16x32_bf16 v[68:71], v[174:177], v[226:229], v[68:71]
	v_mfma_f32_16x16x32_bf16 v[64:67], v[182:185], v[226:229], v[64:67]
	s_barrier
	s_add_i32 s4, s45, s49
	s_add_u32 s98, s2, s28
	s_addc_u32 s99, s3, s29
	s_mov_b32 m0, s4
	ds_read_b128 v[186:189], v169 offset:16384
	ds_read_b128 v[190:193], v169 offset:17408
	ds_read_b128 v[194:197], v169 offset:18432
	ds_read_b128 v[198:201], v169 offset:19456
	ds_read_b128 v[202:205], v169 offset:20480
	ds_read_b128 v[218:221], v169 offset:21504
	ds_read_b128 v[222:225], v169 offset:22528
	ds_read_b128 v[226:229], v169 offset:23552
	global_load_lds_dwordx4 v148, s[2:3]
	s_add_i32 m0, s4, 0x2000
	s_add_u32 s4, s2, 0xb0000
	s_addc_u32 s5, s3, 0
	s_add_i32 s45, s62, s49
	global_load_lds_dwordx4 v136, s[2:3]
	s_mov_b32 m0, s45
	s_add_u32 s100, s8, s28
	s_addc_u32 s101, s9, s29
	global_load_lds_dwordx4 v148, s[4:5]
	s_add_i32 m0, s45, 0x2000
	s_nop 0
	global_load_lds_dwordx4 v136, s[4:5]
	s_mov_b32 m0, s50
	s_nop 0
	global_load_lds_dwordx4 v140, s[8:9]
	s_mov_b32 m0, s51
	s_nop 0
	global_load_lds_dwordx4 v138, s[8:9]
	s_waitcnt vmcnt(8)
	s_waitcnt lgkmcnt(0)
	s_barrier
	s_waitcnt lgkmcnt(0)
	v_mfma_f32_16x16x32_bf16 v[60:63], v[128:131], v[186:189], v[60:63]
	v_mfma_f32_16x16x32_bf16 v[56:59], v[158:161], v[186:189], v[56:59]
	v_mfma_f32_16x16x32_bf16 v[44:47], v[128:131], v[194:197], v[44:47]
	v_mfma_f32_16x16x32_bf16 v[40:43], v[158:161], v[194:197], v[40:43]
	v_mfma_f32_16x16x32_bf16 v[28:31], v[128:131], v[202:205], v[28:31]
	v_mfma_f32_16x16x32_bf16 v[24:27], v[158:161], v[202:205], v[24:27]
	v_mfma_f32_16x16x32_bf16 v[12:15], v[128:131], v[222:225], v[12:15]
	v_mfma_f32_16x16x32_bf16 v[8:11], v[158:161], v[222:225], v[8:11]
	v_mfma_f32_16x16x32_bf16 v[60:63], v[132:135], v[190:193], v[60:63]
	v_mfma_f32_16x16x32_bf16 v[56:59], v[162:165], v[190:193], v[56:59]
	v_mfma_f32_16x16x32_bf16 v[44:47], v[132:135], v[198:201], v[44:47]
	v_mfma_f32_16x16x32_bf16 v[40:43], v[162:165], v[198:201], v[40:43]
	v_mfma_f32_16x16x32_bf16 v[28:31], v[132:135], v[218:221], v[28:31]
	v_mfma_f32_16x16x32_bf16 v[24:27], v[162:165], v[218:221], v[24:27]
	v_mfma_f32_16x16x32_bf16 v[12:15], v[132:135], v[226:229], v[12:15]
	v_mfma_f32_16x16x32_bf16 v[8:11], v[162:165], v[226:229], v[8:11]
	v_mfma_f32_16x16x32_bf16 v[52:55], v[170:173], v[186:189], v[52:55]
	v_mfma_f32_16x16x32_bf16 v[48:51], v[178:181], v[186:189], v[48:51]
	v_mfma_f32_16x16x32_bf16 v[36:39], v[170:173], v[194:197], v[36:39]
	v_mfma_f32_16x16x32_bf16 v[32:35], v[178:181], v[194:197], v[32:35]
	v_mfma_f32_16x16x32_bf16 v[20:23], v[170:173], v[202:205], v[20:23]
	v_mfma_f32_16x16x32_bf16 v[16:19], v[178:181], v[202:205], v[16:19]
	v_mfma_f32_16x16x32_bf16 v[4:7], v[170:173], v[222:225], v[4:7]
	v_mfma_f32_16x16x32_bf16 v[0:3], v[178:181], v[222:225], v[0:3]
	v_mfma_f32_16x16x32_bf16 v[52:55], v[174:177], v[190:193], v[52:55]
	v_mfma_f32_16x16x32_bf16 v[48:51], v[182:185], v[190:193], v[48:51]
	v_mfma_f32_16x16x32_bf16 v[36:39], v[174:177], v[198:201], v[36:39]
	v_mfma_f32_16x16x32_bf16 v[32:35], v[182:185], v[198:201], v[32:35]
	v_mfma_f32_16x16x32_bf16 v[20:23], v[174:177], v[218:221], v[20:23]
	v_mfma_f32_16x16x32_bf16 v[16:19], v[182:185], v[218:221], v[16:19]
	v_mfma_f32_16x16x32_bf16 v[4:7], v[174:177], v[226:229], v[4:7]
	v_mfma_f32_16x16x32_bf16 v[0:3], v[182:185], v[226:229], v[0:3]
	s_barrier
	s_add_i32 s45, 0, 0x18000
	v_add_u32_e32 v150, s45, v168
	s_add_i32 s62, 0, 0x1c000
	ds_read_b128 v[128:131], v150
	ds_read_b128 v[132:135], v150 offset:1024
	ds_read_b128 v[158:161], v150 offset:2048
	ds_read_b128 v[162:165], v150 offset:3072
	v_add_u32_e32 v150, s62, v168
	ds_read_b128 v[170:173], v150
	ds_read_b128 v[174:177], v150 offset:1024
	ds_read_b128 v[178:181], v150 offset:2048
	ds_read_b128 v[182:185], v150 offset:3072
	s_add_u32 s4, s8, 0xb0000
	s_addc_u32 s5, s9, 0
	s_mov_b32 m0, s52
	ds_read_b128 v[186:189], v169 offset:32768
	ds_read_b128 v[190:193], v169 offset:33792
	ds_read_b128 v[194:197], v169 offset:34816
	ds_read_b128 v[198:201], v169 offset:35840
	ds_read_b128 v[202:205], v169 offset:36864
	ds_read_b128 v[218:221], v169 offset:37888
	ds_read_b128 v[222:225], v169 offset:38912
	ds_read_b128 v[226:229], v169 offset:39936
	global_load_lds_dwordx4 v140, s[4:5]
	s_mov_b32 m0, s53
	s_nop 0
	global_load_lds_dwordx4 v138, s[4:5]
	s_waitcnt vmcnt(8)
	s_waitcnt lgkmcnt(0)
	s_barrier
	s_waitcnt lgkmcnt(0)
	v_mfma_f32_16x16x32_bf16 v[124:127], v[128:131], v[186:189], v[124:127]
	v_mfma_f32_16x16x32_bf16 v[120:123], v[158:161], v[186:189], v[120:123]
	v_mfma_f32_16x16x32_bf16 v[108:111], v[128:131], v[194:197], v[108:111]
	v_mfma_f32_16x16x32_bf16 v[104:107], v[158:161], v[194:197], v[104:107]
	v_mfma_f32_16x16x32_bf16 v[92:95], v[128:131], v[202:205], v[92:95]
	v_mfma_f32_16x16x32_bf16 v[88:91], v[158:161], v[202:205], v[88:91]
	v_mfma_f32_16x16x32_bf16 v[76:79], v[128:131], v[222:225], v[76:79]
	v_mfma_f32_16x16x32_bf16 v[72:75], v[158:161], v[222:225], v[72:75]
	v_mfma_f32_16x16x32_bf16 v[124:127], v[132:135], v[190:193], v[124:127]
	v_mfma_f32_16x16x32_bf16 v[120:123], v[162:165], v[190:193], v[120:123]
	v_mfma_f32_16x16x32_bf16 v[108:111], v[132:135], v[198:201], v[108:111]
	v_mfma_f32_16x16x32_bf16 v[104:107], v[162:165], v[198:201], v[104:107]
	v_mfma_f32_16x16x32_bf16 v[92:95], v[132:135], v[218:221], v[92:95]
	v_mfma_f32_16x16x32_bf16 v[88:91], v[162:165], v[218:221], v[88:91]
	v_mfma_f32_16x16x32_bf16 v[76:79], v[132:135], v[226:229], v[76:79]
	v_mfma_f32_16x16x32_bf16 v[72:75], v[162:165], v[226:229], v[72:75]
	v_mfma_f32_16x16x32_bf16 v[116:119], v[170:173], v[186:189], v[116:119]
	v_mfma_f32_16x16x32_bf16 v[112:115], v[178:181], v[186:189], v[112:115]
	v_mfma_f32_16x16x32_bf16 v[100:103], v[170:173], v[194:197], v[100:103]
	v_mfma_f32_16x16x32_bf16 v[96:99], v[178:181], v[194:197], v[96:99]
	v_mfma_f32_16x16x32_bf16 v[84:87], v[170:173], v[202:205], v[84:87]
	v_mfma_f32_16x16x32_bf16 v[80:83], v[178:181], v[202:205], v[80:83]
	v_mfma_f32_16x16x32_bf16 v[68:71], v[170:173], v[222:225], v[68:71]
	v_mfma_f32_16x16x32_bf16 v[64:67], v[178:181], v[222:225], v[64:67]
	v_mfma_f32_16x16x32_bf16 v[116:119], v[174:177], v[190:193], v[116:119]
	v_mfma_f32_16x16x32_bf16 v[112:115], v[182:185], v[190:193], v[112:115]
	v_mfma_f32_16x16x32_bf16 v[100:103], v[174:177], v[198:201], v[100:103]
	v_mfma_f32_16x16x32_bf16 v[96:99], v[182:185], v[198:201], v[96:99]
	v_mfma_f32_16x16x32_bf16 v[84:87], v[174:177], v[218:221], v[84:87]
	v_mfma_f32_16x16x32_bf16 v[80:83], v[182:185], v[218:221], v[80:83]
	v_mfma_f32_16x16x32_bf16 v[68:71], v[174:177], v[226:229], v[68:71]
	v_mfma_f32_16x16x32_bf16 v[64:67], v[182:185], v[226:229], v[64:67]
	s_barrier
	s_add_i32 s4, s45, s49
	s_mov_b32 m0, s4
	ds_read_b128 v[186:189], v169 offset:49152
	ds_read_b128 v[190:193], v169 offset:50176
	ds_read_b128 v[194:197], v169 offset:51200
	ds_read_b128 v[198:201], v169 offset:52224
	ds_read_b128 v[202:205], v169 offset:53248
	ds_read_b128 v[218:221], v169 offset:54272
	ds_read_b128 v[222:225], v169 offset:55296
	ds_read_b128 v[226:229], v169 offset:56320
	global_load_lds_dwordx4 v148, s[98:99]
	s_add_i32 m0, s4, 0x2000
	s_add_u32 s2, s2, 0xb0080
	s_addc_u32 s3, s3, 0
	s_add_i32 s4, s62, s49
	global_load_lds_dwordx4 v136, s[98:99]
	s_mov_b32 m0, s4
	s_nop 0
	global_load_lds_dwordx4 v148, s[2:3]
	s_add_i32 m0, s4, 0x2000
	s_nop 0
	global_load_lds_dwordx4 v136, s[2:3]
	s_mov_b32 m0, s57
	s_nop 0
	global_load_lds_dwordx4 v140, s[100:101]
	s_mov_b32 m0, s58
	s_nop 0
	global_load_lds_dwordx4 v138, s[100:101]
	s_waitcnt vmcnt(8)
	s_waitcnt lgkmcnt(0)
	s_barrier
	s_waitcnt lgkmcnt(0)
	v_mfma_f32_16x16x32_bf16 v[60:63], v[128:131], v[186:189], v[60:63]
	v_mfma_f32_16x16x32_bf16 v[56:59], v[158:161], v[186:189], v[56:59]
	v_mfma_f32_16x16x32_bf16 v[44:47], v[128:131], v[194:197], v[44:47]
	v_mfma_f32_16x16x32_bf16 v[40:43], v[158:161], v[194:197], v[40:43]
	v_mfma_f32_16x16x32_bf16 v[28:31], v[128:131], v[202:205], v[28:31]
	v_mfma_f32_16x16x32_bf16 v[24:27], v[158:161], v[202:205], v[24:27]
	v_mfma_f32_16x16x32_bf16 v[12:15], v[128:131], v[222:225], v[12:15]
	v_mfma_f32_16x16x32_bf16 v[8:11], v[158:161], v[222:225], v[8:11]
	v_mfma_f32_16x16x32_bf16 v[60:63], v[132:135], v[190:193], v[60:63]
	v_mfma_f32_16x16x32_bf16 v[56:59], v[162:165], v[190:193], v[56:59]
	v_mfma_f32_16x16x32_bf16 v[44:47], v[132:135], v[198:201], v[44:47]
	v_mfma_f32_16x16x32_bf16 v[40:43], v[162:165], v[198:201], v[40:43]
	v_mfma_f32_16x16x32_bf16 v[28:31], v[132:135], v[218:221], v[28:31]
	v_mfma_f32_16x16x32_bf16 v[24:27], v[162:165], v[218:221], v[24:27]
	v_mfma_f32_16x16x32_bf16 v[12:15], v[132:135], v[226:229], v[12:15]
	v_mfma_f32_16x16x32_bf16 v[8:11], v[162:165], v[226:229], v[8:11]
	v_mfma_f32_16x16x32_bf16 v[52:55], v[170:173], v[186:189], v[52:55]
	v_mfma_f32_16x16x32_bf16 v[48:51], v[178:181], v[186:189], v[48:51]
	v_mfma_f32_16x16x32_bf16 v[36:39], v[170:173], v[194:197], v[36:39]
	v_mfma_f32_16x16x32_bf16 v[32:35], v[178:181], v[194:197], v[32:35]
	v_mfma_f32_16x16x32_bf16 v[20:23], v[170:173], v[202:205], v[20:23]
	v_mfma_f32_16x16x32_bf16 v[16:19], v[178:181], v[202:205], v[16:19]
	v_mfma_f32_16x16x32_bf16 v[4:7], v[170:173], v[222:225], v[4:7]
	v_mfma_f32_16x16x32_bf16 v[0:3], v[178:181], v[222:225], v[0:3]
	v_mfma_f32_16x16x32_bf16 v[52:55], v[174:177], v[190:193], v[52:55]
	v_mfma_f32_16x16x32_bf16 v[48:51], v[182:185], v[190:193], v[48:51]
	v_mfma_f32_16x16x32_bf16 v[36:39], v[174:177], v[198:201], v[36:39]
	v_mfma_f32_16x16x32_bf16 v[32:35], v[182:185], v[198:201], v[32:35]
	v_mfma_f32_16x16x32_bf16 v[20:23], v[174:177], v[218:221], v[20:23]
	v_mfma_f32_16x16x32_bf16 v[16:19], v[182:185], v[218:221], v[16:19]
	v_mfma_f32_16x16x32_bf16 v[4:7], v[174:177], v[226:229], v[4:7]
	v_mfma_f32_16x16x32_bf16 v[0:3], v[182:185], v[226:229], v[0:3]
	s_barrier
	s_add_i32 s44, s44, 2
	s_add_u32 s42, s42, 0x100
	s_addc_u32 s43, s43, 0
	s_cmp_gt_u32 s44, 41
	s_mov_b64 s[4:5], s[0:1]
	s_cbranch_scc0 .LBB0_360
	s_and_b64 vcc, exec, s[30:31]
	s_cbranch_vccz .LBB0_363
	s_barrier

.Lz_skip_2:
	s_waitcnt vmcnt(8)
	s_waitcnt lgkmcnt(0)
	s_barrier
	s_waitcnt lgkmcnt(0)
	v_mfma_f32_16x16x32_bf16 v[124:127], v[140:143], v[190:193], v[124:127]
	v_mfma_f32_16x16x32_bf16 v[120:123], v[162:165], v[190:193], v[120:123]
	v_mfma_f32_16x16x32_bf16 v[108:111], v[140:143], v[198:201], v[108:111]
	v_mfma_f32_16x16x32_bf16 v[104:107], v[162:165], v[198:201], v[104:107]
	v_mfma_f32_16x16x32_bf16 v[92:95], v[140:143], v[218:221], v[92:95]
	v_mfma_f32_16x16x32_bf16 v[88:91], v[162:165], v[218:221], v[88:91]
	v_mfma_f32_16x16x32_bf16 v[76:79], v[140:143], v[226:229], v[76:79]
	v_mfma_f32_16x16x32_bf16 v[72:75], v[162:165], v[226:229], v[72:75]
	v_mfma_f32_16x16x32_bf16 v[124:127], v[158:161], v[194:197], v[124:127]
	v_mfma_f32_16x16x32_bf16 v[120:123], v[166:169], v[194:197], v[120:123]
	v_mfma_f32_16x16x32_bf16 v[108:111], v[158:161], v[202:205], v[108:111]
	v_mfma_f32_16x16x32_bf16 v[104:107], v[166:169], v[202:205], v[104:107]
	v_mfma_f32_16x16x32_bf16 v[92:95], v[158:161], v[222:225], v[92:95]
	v_mfma_f32_16x16x32_bf16 v[88:91], v[166:169], v[222:225], v[88:91]
	v_mfma_f32_16x16x32_bf16 v[76:79], v[158:161], v[230:233], v[76:79]
	v_mfma_f32_16x16x32_bf16 v[72:75], v[166:169], v[230:233], v[72:75]
	v_mfma_f32_16x16x32_bf16 v[116:119], v[174:177], v[190:193], v[116:119]
	v_mfma_f32_16x16x32_bf16 v[112:115], v[182:185], v[190:193], v[112:115]
	v_mfma_f32_16x16x32_bf16 v[100:103], v[174:177], v[198:201], v[100:103]
	v_mfma_f32_16x16x32_bf16 v[96:99], v[182:185], v[198:201], v[96:99]
	v_mfma_f32_16x16x32_bf16 v[84:87], v[174:177], v[218:221], v[84:87]
	v_mfma_f32_16x16x32_bf16 v[80:83], v[182:185], v[218:221], v[80:83]
	v_mfma_f32_16x16x32_bf16 v[68:71], v[174:177], v[226:229], v[68:71]
	v_mfma_f32_16x16x32_bf16 v[64:67], v[182:185], v[226:229], v[64:67]
	v_mfma_f32_16x16x32_bf16 v[116:119], v[178:181], v[194:197], v[116:119]
	v_mfma_f32_16x16x32_bf16 v[112:115], v[186:189], v[194:197], v[112:115]
	v_mfma_f32_16x16x32_bf16 v[100:103], v[178:181], v[202:205], v[100:103]
	v_mfma_f32_16x16x32_bf16 v[96:99], v[186:189], v[202:205], v[96:99]
	v_mfma_f32_16x16x32_bf16 v[84:87], v[178:181], v[222:225], v[84:87]
	v_mfma_f32_16x16x32_bf16 v[80:83], v[186:189], v[222:225], v[80:83]
	v_mfma_f32_16x16x32_bf16 v[68:71], v[178:181], v[230:233], v[68:71]
	v_mfma_f32_16x16x32_bf16 v[64:67], v[186:189], v[230:233], v[64:67]
	s_barrier
	s_add_i32 s44, s44, s56
	s_add_u32 s98, s12, s28
	s_addc_u32 s99, s13, s29
	s_mov_b32 m0, s44
	ds_read_b128 v[190:193], v145 offset:16384
	ds_read_b128 v[194:197], v145 offset:17408
	ds_read_b128 v[198:201], v145 offset:18432
	ds_read_b128 v[202:205], v145 offset:19456
	ds_read_b128 v[218:221], v145 offset:20480
	ds_read_b128 v[222:225], v145 offset:21504
	ds_read_b128 v[226:229], v145 offset:22528
	ds_read_b128 v[230:233], v145 offset:23552
	global_load_lds_dwordx4 v132, s[12:13]
	s_add_i32 m0, s44, 0x2000
	s_add_u32 s44, s12, 0x40000
	s_addc_u32 s45, s13, 0
	s_add_i32 s46, s46, s56
	global_load_lds_dwordx4 v128, s[12:13]
	s_mov_b32 m0, s46
	s_add_u32 s100, s14, s28
	s_addc_u32 s101, s15, s29
	global_load_lds_dwordx4 v132, s[44:45]
	s_add_i32 m0, s46, 0x2000
	s_nop 0
	global_load_lds_dwordx4 v128, s[44:45]
	s_mov_b32 m0, s57
	s_nop 0
	global_load_lds_dwordx4 v134, s[14:15]
	s_mov_b32 m0, s58
	s_nop 0
	global_load_lds_dwordx4 v130, s[14:15]
	s_waitcnt vmcnt(8)
	s_waitcnt lgkmcnt(0)
	s_barrier
	s_waitcnt lgkmcnt(0)
	v_mfma_f32_16x16x32_bf16 v[60:63], v[140:143], v[190:193], v[60:63]
	v_mfma_f32_16x16x32_bf16 v[56:59], v[162:165], v[190:193], v[56:59]
	v_mfma_f32_16x16x32_bf16 v[44:47], v[140:143], v[198:201], v[44:47]
	v_mfma_f32_16x16x32_bf16 v[40:43], v[162:165], v[198:201], v[40:43]
	v_mfma_f32_16x16x32_bf16 v[28:31], v[140:143], v[218:221], v[28:31]
	v_mfma_f32_16x16x32_bf16 v[24:27], v[162:165], v[218:221], v[24:27]
	v_mfma_f32_16x16x32_bf16 v[12:15], v[140:143], v[226:229], v[12:15]
	v_mfma_f32_16x16x32_bf16 v[8:11], v[162:165], v[226:229], v[8:11]
	v_mfma_f32_16x16x32_bf16 v[60:63], v[158:161], v[194:197], v[60:63]
	v_mfma_f32_16x16x32_bf16 v[56:59], v[166:169], v[194:197], v[56:59]
	v_mfma_f32_16x16x32_bf16 v[44:47], v[158:161], v[202:205], v[44:47]
	v_mfma_f32_16x16x32_bf16 v[40:43], v[166:169], v[202:205], v[40:43]
	v_mfma_f32_16x16x32_bf16 v[28:31], v[158:161], v[222:225], v[28:31]
	v_mfma_f32_16x16x32_bf16 v[24:27], v[166:169], v[222:225], v[24:27]
	v_mfma_f32_16x16x32_bf16 v[12:15], v[158:161], v[230:233], v[12:15]
	v_mfma_f32_16x16x32_bf16 v[8:11], v[166:169], v[230:233], v[8:11]
	v_mfma_f32_16x16x32_bf16 v[52:55], v[174:177], v[190:193], v[52:55]
	v_mfma_f32_16x16x32_bf16 v[48:51], v[182:185], v[190:193], v[48:51]
	v_mfma_f32_16x16x32_bf16 v[36:39], v[174:177], v[198:201], v[36:39]
	v_mfma_f32_16x16x32_bf16 v[32:35], v[182:185], v[198:201], v[32:35]
	v_mfma_f32_16x16x32_bf16 v[20:23], v[174:177], v[218:221], v[20:23]
	v_mfma_f32_16x16x32_bf16 v[16:19], v[182:185], v[218:221], v[16:19]
	v_mfma_f32_16x16x32_bf16 v[4:7], v[174:177], v[226:229], v[4:7]
	v_mfma_f32_16x16x32_bf16 v[0:3], v[182:185], v[226:229], v[0:3]
	v_mfma_f32_16x16x32_bf16 v[52:55], v[178:181], v[194:197], v[52:55]
	v_mfma_f32_16x16x32_bf16 v[48:51], v[186:189], v[194:197], v[48:51]
	v_mfma_f32_16x16x32_bf16 v[36:39], v[178:181], v[202:205], v[36:39]
	v_mfma_f32_16x16x32_bf16 v[32:35], v[186:189], v[202:205], v[32:35]
	v_mfma_f32_16x16x32_bf16 v[20:23], v[178:181], v[222:225], v[20:23]
	v_mfma_f32_16x16x32_bf16 v[16:19], v[186:189], v[222:225], v[16:19]
	v_mfma_f32_16x16x32_bf16 v[4:7], v[178:181], v[230:233], v[4:7]
	v_mfma_f32_16x16x32_bf16 v[0:3], v[186:189], v[230:233], v[0:3]
	s_barrier
	s_add_i32 s44, 0, 0x18000
	v_add_u32_e32 v148, s44, v144
	s_add_i32 s45, 0, 0x1c000
	ds_read_b128 v[140:143], v148
	ds_read_b128 v[158:161], v148 offset:1024
	ds_read_b128 v[162:165], v148 offset:2048
	ds_read_b128 v[166:169], v148 offset:3072
	v_add_u32_e32 v148, s45, v144
	ds_read_b128 v[174:177], v148
	ds_read_b128 v[178:181], v148 offset:1024
	ds_read_b128 v[182:185], v148 offset:2048
	ds_read_b128 v[186:189], v148 offset:3072
	s_add_u32 s14, s14, 0x40000
	s_addc_u32 s15, s15, 0
	s_mov_b32 m0, s59
	ds_read_b128 v[190:193], v145 offset:32768
	ds_read_b128 v[194:197], v145 offset:33792
	ds_read_b128 v[198:201], v145 offset:34816
	ds_read_b128 v[202:205], v145 offset:35840
	ds_read_b128 v[218:221], v145 offset:36864
	ds_read_b128 v[222:225], v145 offset:37888
	ds_read_b128 v[226:229], v145 offset:38912
	ds_read_b128 v[230:233], v145 offset:39936
	global_load_lds_dwordx4 v134, s[14:15]
	s_mov_b32 m0, s60
	s_nop 0
	global_load_lds_dwordx4 v130, s[14:15]
	s_waitcnt vmcnt(8)
	s_waitcnt lgkmcnt(0)
	s_barrier
	s_waitcnt lgkmcnt(0)
	v_mfma_f32_16x16x32_bf16 v[124:127], v[140:143], v[190:193], v[124:127]
	v_mfma_f32_16x16x32_bf16 v[120:123], v[162:165], v[190:193], v[120:123]
	v_mfma_f32_16x16x32_bf16 v[108:111], v[140:143], v[198:201], v[108:111]
	v_mfma_f32_16x16x32_bf16 v[104:107], v[162:165], v[198:201], v[104:107]
	v_mfma_f32_16x16x32_bf16 v[92:95], v[140:143], v[218:221], v[92:95]
	v_mfma_f32_16x16x32_bf16 v[88:91], v[162:165], v[218:221], v[88:91]
	v_mfma_f32_16x16x32_bf16 v[76:79], v[140:143], v[226:229], v[76:79]
	v_mfma_f32_16x16x32_bf16 v[72:75], v[162:165], v[226:229], v[72:75]
	v_mfma_f32_16x16x32_bf16 v[124:127], v[158:161], v[194:197], v[124:127]
	v_mfma_f32_16x16x32_bf16 v[120:123], v[166:169], v[194:197], v[120:123]
	v_mfma_f32_16x16x32_bf16 v[108:111], v[158:161], v[202:205], v[108:111]
	v_mfma_f32_16x16x32_bf16 v[104:107], v[166:169], v[202:205], v[104:107]
	v_mfma_f32_16x16x32_bf16 v[92:95], v[158:161], v[222:225], v[92:95]
	v_mfma_f32_16x16x32_bf16 v[88:91], v[166:169], v[222:225], v[88:91]
	v_mfma_f32_16x16x32_bf16 v[76:79], v[158:161], v[230:233], v[76:79]
	v_mfma_f32_16x16x32_bf16 v[72:75], v[166:169], v[230:233], v[72:75]
	v_mfma_f32_16x16x32_bf16 v[116:119], v[174:177], v[190:193], v[116:119]
	v_mfma_f32_16x16x32_bf16 v[112:115], v[182:185], v[190:193], v[112:115]
	v_mfma_f32_16x16x32_bf16 v[100:103], v[174:177], v[198:201], v[100:103]
	v_mfma_f32_16x16x32_bf16 v[96:99], v[182:185], v[198:201], v[96:99]
	v_mfma_f32_16x16x32_bf16 v[84:87], v[174:177], v[218:221], v[84:87]
	v_mfma_f32_16x16x32_bf16 v[80:83], v[182:185], v[218:221], v[80:83]
	v_mfma_f32_16x16x32_bf16 v[68:71], v[174:177], v[226:229], v[68:71]
	v_mfma_f32_16x16x32_bf16 v[64:67], v[182:185], v[226:229], v[64:67]
	v_mfma_f32_16x16x32_bf16 v[116:119], v[178:181], v[194:197], v[116:119]
	v_mfma_f32_16x16x32_bf16 v[112:115], v[186:189], v[194:197], v[112:115]
	v_mfma_f32_16x16x32_bf16 v[100:103], v[178:181], v[202:205], v[100:103]
	v_mfma_f32_16x16x32_bf16 v[96:99], v[186:189], v[202:205], v[96:99]
	v_mfma_f32_16x16x32_bf16 v[84:87], v[178:181], v[222:225], v[84:87]
	v_mfma_f32_16x16x32_bf16 v[80:83], v[186:189], v[222:225], v[80:83]
	v_mfma_f32_16x16x32_bf16 v[68:71], v[178:181], v[230:233], v[68:71]
	v_mfma_f32_16x16x32_bf16 v[64:67], v[186:189], v[230:233], v[64:67]
	s_barrier
	s_add_i32 s14, s44, s56
	s_mov_b32 m0, s14
	ds_read_b128 v[190:193], v145 offset:49152
	ds_read_b128 v[194:197], v145 offset:50176
	ds_read_b128 v[198:201], v145 offset:51200
	ds_read_b128 v[202:205], v145 offset:52224
	ds_read_b128 v[218:221], v145 offset:53248
	ds_read_b128 v[222:225], v145 offset:54272
	ds_read_b128 v[226:229], v145 offset:55296
	ds_read_b128 v[230:233], v145 offset:56320
	global_load_lds_dwordx4 v132, s[98:99]
	s_add_i32 m0, s14, 0x2000
	s_add_u32 s12, s12, 0x40080
	s_addc_u32 s13, s13, 0
	s_add_i32 s14, s45, s56
	global_load_lds_dwordx4 v128, s[98:99]
	s_mov_b32 m0, s14
	s_nop 0
	global_load_lds_dwordx4 v132, s[12:13]
	s_add_i32 m0, s14, 0x2000
	s_nop 0
	global_load_lds_dwordx4 v128, s[12:13]
	s_mov_b32 m0, s72
	s_nop 0
	global_load_lds_dwordx4 v134, s[100:101]
	s_mov_b32 m0, s73
	s_nop 0
	global_load_lds_dwordx4 v130, s[100:101]
	s_waitcnt vmcnt(8)
	s_waitcnt lgkmcnt(0)
	s_barrier
	s_waitcnt lgkmcnt(0)
	v_mfma_f32_16x16x32_bf16 v[60:63], v[140:143], v[190:193], v[60:63]
	v_mfma_f32_16x16x32_bf16 v[56:59], v[162:165], v[190:193], v[56:59]
	v_mfma_f32_16x16x32_bf16 v[44:47], v[140:143], v[198:201], v[44:47]
	v_mfma_f32_16x16x32_bf16 v[40:43], v[162:165], v[198:201], v[40:43]
	v_mfma_f32_16x16x32_bf16 v[28:31], v[140:143], v[218:221], v[28:31]
	v_mfma_f32_16x16x32_bf16 v[24:27], v[162:165], v[218:221], v[24:27]
	v_mfma_f32_16x16x32_bf16 v[12:15], v[140:143], v[226:229], v[12:15]
	v_mfma_f32_16x16x32_bf16 v[8:11], v[162:165], v[226:229], v[8:11]
	v_mfma_f32_16x16x32_bf16 v[60:63], v[158:161], v[194:197], v[60:63]
	v_mfma_f32_16x16x32_bf16 v[56:59], v[166:169], v[194:197], v[56:59]
	v_mfma_f32_16x16x32_bf16 v[44:47], v[158:161], v[202:205], v[44:47]
	v_mfma_f32_16x16x32_bf16 v[40:43], v[166:169], v[202:205], v[40:43]
	v_mfma_f32_16x16x32_bf16 v[28:31], v[158:161], v[222:225], v[28:31]
	v_mfma_f32_16x16x32_bf16 v[24:27], v[166:169], v[222:225], v[24:27]
	v_mfma_f32_16x16x32_bf16 v[12:15], v[158:161], v[230:233], v[12:15]
	v_mfma_f32_16x16x32_bf16 v[8:11], v[166:169], v[230:233], v[8:11]
	v_mfma_f32_16x16x32_bf16 v[52:55], v[174:177], v[190:193], v[52:55]
	v_mfma_f32_16x16x32_bf16 v[48:51], v[182:185], v[190:193], v[48:51]
	v_mfma_f32_16x16x32_bf16 v[36:39], v[174:177], v[198:201], v[36:39]
	v_mfma_f32_16x16x32_bf16 v[32:35], v[182:185], v[198:201], v[32:35]
	v_mfma_f32_16x16x32_bf16 v[20:23], v[174:177], v[218:221], v[20:23]
	v_mfma_f32_16x16x32_bf16 v[16:19], v[182:185], v[218:221], v[16:19]
	v_mfma_f32_16x16x32_bf16 v[4:7], v[174:177], v[226:229], v[4:7]
	v_mfma_f32_16x16x32_bf16 v[0:3], v[182:185], v[226:229], v[0:3]
	v_mfma_f32_16x16x32_bf16 v[52:55], v[178:181], v[194:197], v[52:55]
	v_mfma_f32_16x16x32_bf16 v[48:51], v[186:189], v[194:197], v[48:51]
	v_mfma_f32_16x16x32_bf16 v[36:39], v[178:181], v[202:205], v[36:39]
	v_mfma_f32_16x16x32_bf16 v[32:35], v[186:189], v[202:205], v[32:35]
	v_mfma_f32_16x16x32_bf16 v[20:23], v[178:181], v[222:225], v[20:23]
	v_mfma_f32_16x16x32_bf16 v[16:19], v[186:189], v[222:225], v[16:19]
	v_mfma_f32_16x16x32_bf16 v[4:7], v[178:181], v[230:233], v[4:7]
	v_mfma_f32_16x16x32_bf16 v[0:3], v[186:189], v[230:233], v[0:3]
	s_barrier
	s_add_i32 s43, s43, 2
	s_add_u32 s10, s10, 0x100
	s_addc_u32 s11, s11, 0
	s_add_u32 s37, s37, 0x100
	s_addc_u32 s42, s42, 0
	s_cmp_gt_u32 s43, 13
	s_cbranch_scc0 .LBB0_588
	s_and_b64 vcc, exec, s[26:27]
	s_cbranch_vccz .LBB0_591
	s_barrier

.Lz_skip_3:
	s_waitcnt vmcnt(8)
	s_waitcnt lgkmcnt(0)
	s_barrier
	s_waitcnt lgkmcnt(0)
	v_mfma_f32_16x16x32_bf16 v[124:127], v[128:131], v[184:187], v[124:127]
	v_mfma_f32_16x16x32_bf16 v[92:95], v[136:139], v[184:187], v[92:95]
	v_mfma_f32_16x16x32_bf16 v[120:123], v[128:131], v[192:195], v[120:123]
	v_mfma_f32_16x16x32_bf16 v[88:91], v[136:139], v[192:195], v[88:91]
	v_mfma_f32_16x16x32_bf16 v[116:119], v[128:131], v[200:203], v[116:119]
	v_mfma_f32_16x16x32_bf16 v[84:87], v[136:139], v[200:203], v[84:87]
	v_mfma_f32_16x16x32_bf16 v[112:115], v[128:131], v[222:225], v[112:115]
	v_mfma_f32_16x16x32_bf16 v[80:83], v[136:139], v[222:225], v[80:83]
	v_mfma_f32_16x16x32_bf16 v[124:127], v[132:135], v[188:191], v[124:127]
	v_mfma_f32_16x16x32_bf16 v[92:95], v[140:143], v[188:191], v[92:95]
	v_mfma_f32_16x16x32_bf16 v[120:123], v[132:135], v[196:199], v[120:123]
	v_mfma_f32_16x16x32_bf16 v[88:91], v[140:143], v[196:199], v[88:91]
	v_mfma_f32_16x16x32_bf16 v[116:119], v[132:135], v[218:221], v[116:119]
	v_mfma_f32_16x16x32_bf16 v[84:87], v[140:143], v[218:221], v[84:87]
	v_mfma_f32_16x16x32_bf16 v[112:115], v[132:135], v[226:229], v[112:115]
	v_mfma_f32_16x16x32_bf16 v[80:83], v[140:143], v[226:229], v[80:83]
	v_mfma_f32_16x16x32_bf16 v[60:63], v[164:167], v[184:187], v[60:63]
	v_mfma_f32_16x16x32_bf16 v[28:31], v[176:179], v[184:187], v[28:31]
	v_mfma_f32_16x16x32_bf16 v[56:59], v[164:167], v[192:195], v[56:59]
	v_mfma_f32_16x16x32_bf16 v[24:27], v[176:179], v[192:195], v[24:27]
	v_mfma_f32_16x16x32_bf16 v[52:55], v[164:167], v[200:203], v[52:55]
	v_mfma_f32_16x16x32_bf16 v[20:23], v[176:179], v[200:203], v[20:23]
	v_mfma_f32_16x16x32_bf16 v[48:51], v[164:167], v[222:225], v[48:51]
	v_mfma_f32_16x16x32_bf16 v[16:19], v[176:179], v[222:225], v[16:19]
	v_mfma_f32_16x16x32_bf16 v[60:63], v[168:171], v[188:191], v[60:63]
	v_mfma_f32_16x16x32_bf16 v[28:31], v[180:183], v[188:191], v[28:31]
	v_mfma_f32_16x16x32_bf16 v[56:59], v[168:171], v[196:199], v[56:59]
	v_mfma_f32_16x16x32_bf16 v[24:27], v[180:183], v[196:199], v[24:27]
	v_mfma_f32_16x16x32_bf16 v[52:55], v[168:171], v[218:221], v[52:55]
	v_mfma_f32_16x16x32_bf16 v[20:23], v[180:183], v[218:221], v[20:23]
	v_mfma_f32_16x16x32_bf16 v[48:51], v[168:171], v[226:229], v[48:51]
	v_mfma_f32_16x16x32_bf16 v[16:19], v[180:183], v[226:229], v[16:19]
	s_barrier
	s_add_i32 s53, s53, s36
	s_add_u32 s98, s30, s28
	s_addc_u32 s99, s31, s29
	s_mov_b32 m0, s53
	ds_read_b128 v[184:187], v174 offset:16384
	ds_read_b128 v[188:191], v174 offset:17408
	ds_read_b128 v[192:195], v174 offset:18432
	ds_read_b128 v[196:199], v174 offset:19456
	ds_read_b128 v[200:203], v174 offset:20480
	ds_read_b128 v[218:221], v174 offset:21504
	ds_read_b128 v[222:225], v174 offset:22528
	ds_read_b128 v[226:229], v174 offset:23552
	global_load_lds_dwordx4 v158, s[30:31]
	s_add_i32 m0, s53, 0x2000
	s_add_u32 s54, s30, 0x40000
	s_addc_u32 s55, s31, 0
	s_add_i32 s53, s56, s36
	global_load_lds_dwordx4 v144, s[30:31]
	s_mov_b32 m0, s53
	s_add_u32 s100, s34, s28
	s_addc_u32 s101, s35, s29
	global_load_lds_dwordx4 v158, s[54:55]
	s_add_i32 m0, s53, 0x2000
	s_nop 0
	global_load_lds_dwordx4 v144, s[54:55]
	s_mov_b32 m0, s37
	s_nop 0
	global_load_lds_dwordx4 v148, s[34:35]
	s_mov_b32 m0, s38
	s_nop 0
	global_load_lds_dwordx4 v146, s[34:35]
	s_waitcnt vmcnt(8)
	s_waitcnt lgkmcnt(0)
	s_barrier
	s_waitcnt lgkmcnt(0)
	v_mfma_f32_16x16x32_bf16 v[108:111], v[128:131], v[184:187], v[108:111]
	v_mfma_f32_16x16x32_bf16 v[76:79], v[136:139], v[184:187], v[76:79]
	v_mfma_f32_16x16x32_bf16 v[104:107], v[128:131], v[192:195], v[104:107]
	v_mfma_f32_16x16x32_bf16 v[72:75], v[136:139], v[192:195], v[72:75]
	v_mfma_f32_16x16x32_bf16 v[100:103], v[128:131], v[200:203], v[100:103]
	v_mfma_f32_16x16x32_bf16 v[68:71], v[136:139], v[200:203], v[68:71]
	v_mfma_f32_16x16x32_bf16 v[96:99], v[128:131], v[222:225], v[96:99]
	v_mfma_f32_16x16x32_bf16 v[64:67], v[136:139], v[222:225], v[64:67]
	v_mfma_f32_16x16x32_bf16 v[108:111], v[132:135], v[188:191], v[108:111]
	v_mfma_f32_16x16x32_bf16 v[76:79], v[140:143], v[188:191], v[76:79]
	v_mfma_f32_16x16x32_bf16 v[104:107], v[132:135], v[196:199], v[104:107]
	v_mfma_f32_16x16x32_bf16 v[72:75], v[140:143], v[196:199], v[72:75]
	v_mfma_f32_16x16x32_bf16 v[100:103], v[132:135], v[218:221], v[100:103]
	v_mfma_f32_16x16x32_bf16 v[68:71], v[140:143], v[218:221], v[68:71]
	v_mfma_f32_16x16x32_bf16 v[96:99], v[132:135], v[226:229], v[96:99]
	v_mfma_f32_16x16x32_bf16 v[64:67], v[140:143], v[226:229], v[64:67]
	v_mfma_f32_16x16x32_bf16 v[44:47], v[164:167], v[184:187], v[44:47]
	v_mfma_f32_16x16x32_bf16 v[12:15], v[176:179], v[184:187], v[12:15]
	v_mfma_f32_16x16x32_bf16 v[40:43], v[164:167], v[192:195], v[40:43]
	v_mfma_f32_16x16x32_bf16 v[8:11], v[176:179], v[192:195], v[8:11]
	v_mfma_f32_16x16x32_bf16 v[36:39], v[164:167], v[200:203], v[36:39]
	v_mfma_f32_16x16x32_bf16 v[4:7], v[176:179], v[200:203], v[4:7]
	v_mfma_f32_16x16x32_bf16 v[32:35], v[164:167], v[222:225], v[32:35]
	v_mfma_f32_16x16x32_bf16 v[0:3], v[176:179], v[222:225], v[0:3]
	v_mfma_f32_16x16x32_bf16 v[44:47], v[168:171], v[188:191], v[44:47]
	v_mfma_f32_16x16x32_bf16 v[12:15], v[180:183], v[188:191], v[12:15]
	v_mfma_f32_16x16x32_bf16 v[40:43], v[168:171], v[196:199], v[40:43]
	v_mfma_f32_16x16x32_bf16 v[8:11], v[180:183], v[196:199], v[8:11]
	v_mfma_f32_16x16x32_bf16 v[36:39], v[168:171], v[218:221], v[36:39]
	v_mfma_f32_16x16x32_bf16 v[4:7], v[180:183], v[218:221], v[4:7]
	v_mfma_f32_16x16x32_bf16 v[32:35], v[168:171], v[226:229], v[32:35]
	v_mfma_f32_16x16x32_bf16 v[0:3], v[180:183], v[226:229], v[0:3]
	s_barrier
	s_add_i32 s53, 0, 0x18000
	s_add_i32 s54, 0, 0x1c000
	v_add_u32_e32 v140, s53, v173
	v_add_u32_e32 v150, s54, v173
	ds_read_b128 v[128:131], v140
	ds_read_b128 v[132:135], v140 offset:1024
	ds_read_b128 v[136:139], v140 offset:2048
	ds_read_b128 v[140:143], v140 offset:3072
	ds_read_b128 v[164:167], v150
	ds_read_b128 v[168:171], v150 offset:1024
	ds_read_b128 v[176:179], v150 offset:2048
	ds_read_b128 v[180:183], v150 offset:3072
	s_add_u32 s34, s34, 0x40000
	s_addc_u32 s35, s35, 0
	s_mov_b32 m0, s39
	ds_read_b128 v[184:187], v174 offset:32768
	ds_read_b128 v[188:191], v174 offset:33792
	ds_read_b128 v[192:195], v174 offset:34816
	ds_read_b128 v[196:199], v174 offset:35840
	ds_read_b128 v[200:203], v174 offset:36864
	ds_read_b128 v[218:221], v174 offset:37888
	ds_read_b128 v[222:225], v174 offset:38912
	ds_read_b128 v[226:229], v174 offset:39936
	global_load_lds_dwordx4 v148, s[34:35]
	s_mov_b32 m0, s40
	s_nop 0
	global_load_lds_dwordx4 v146, s[34:35]
	s_waitcnt vmcnt(8)
	s_waitcnt lgkmcnt(0)
	s_barrier
	s_waitcnt lgkmcnt(0)
	v_mfma_f32_16x16x32_bf16 v[124:127], v[128:131], v[184:187], v[124:127]
	v_mfma_f32_16x16x32_bf16 v[92:95], v[136:139], v[184:187], v[92:95]
	v_mfma_f32_16x16x32_bf16 v[120:123], v[128:131], v[192:195], v[120:123]
	v_mfma_f32_16x16x32_bf16 v[88:91], v[136:139], v[192:195], v[88:91]
	v_mfma_f32_16x16x32_bf16 v[116:119], v[128:131], v[200:203], v[116:119]
	v_mfma_f32_16x16x32_bf16 v[84:87], v[136:139], v[200:203], v[84:87]
	v_mfma_f32_16x16x32_bf16 v[112:115], v[128:131], v[222:225], v[112:115]
	v_mfma_f32_16x16x32_bf16 v[80:83], v[136:139], v[222:225], v[80:83]
	v_mfma_f32_16x16x32_bf16 v[124:127], v[132:135], v[188:191], v[124:127]
	v_mfma_f32_16x16x32_bf16 v[92:95], v[140:143], v[188:191], v[92:95]
	v_mfma_f32_16x16x32_bf16 v[120:123], v[132:135], v[196:199], v[120:123]
	v_mfma_f32_16x16x32_bf16 v[88:91], v[140:143], v[196:199], v[88:91]
	v_mfma_f32_16x16x32_bf16 v[116:119], v[132:135], v[218:221], v[116:119]
	v_mfma_f32_16x16x32_bf16 v[84:87], v[140:143], v[218:221], v[84:87]
	v_mfma_f32_16x16x32_bf16 v[112:115], v[132:135], v[226:229], v[112:115]
	v_mfma_f32_16x16x32_bf16 v[80:83], v[140:143], v[226:229], v[80:83]
	v_mfma_f32_16x16x32_bf16 v[60:63], v[164:167], v[184:187], v[60:63]
	v_mfma_f32_16x16x32_bf16 v[28:31], v[176:179], v[184:187], v[28:31]
	v_mfma_f32_16x16x32_bf16 v[56:59], v[164:167], v[192:195], v[56:59]
	v_mfma_f32_16x16x32_bf16 v[24:27], v[176:179], v[192:195], v[24:27]
	v_mfma_f32_16x16x32_bf16 v[52:55], v[164:167], v[200:203], v[52:55]
	v_mfma_f32_16x16x32_bf16 v[20:23], v[176:179], v[200:203], v[20:23]
	v_mfma_f32_16x16x32_bf16 v[48:51], v[164:167], v[222:225], v[48:51]
	v_mfma_f32_16x16x32_bf16 v[16:19], v[176:179], v[222:225], v[16:19]
	v_mfma_f32_16x16x32_bf16 v[60:63], v[168:171], v[188:191], v[60:63]
	v_mfma_f32_16x16x32_bf16 v[28:31], v[180:183], v[188:191], v[28:31]
	v_mfma_f32_16x16x32_bf16 v[56:59], v[168:171], v[196:199], v[56:59]
	v_mfma_f32_16x16x32_bf16 v[24:27], v[180:183], v[196:199], v[24:27]
	v_mfma_f32_16x16x32_bf16 v[52:55], v[168:171], v[218:221], v[52:55]
	v_mfma_f32_16x16x32_bf16 v[20:23], v[180:183], v[218:221], v[20:23]
	v_mfma_f32_16x16x32_bf16 v[48:51], v[168:171], v[226:229], v[48:51]
	v_mfma_f32_16x16x32_bf16 v[16:19], v[180:183], v[226:229], v[16:19]
	s_barrier
	s_add_i32 s34, s53, s36
	s_mov_b32 m0, s34
	ds_read_b128 v[184:187], v174 offset:49152
	ds_read_b128 v[188:191], v174 offset:50176
	ds_read_b128 v[192:195], v174 offset:51200
	ds_read_b128 v[196:199], v174 offset:52224
	ds_read_b128 v[200:203], v174 offset:53248
	ds_read_b128 v[218:221], v174 offset:54272
	ds_read_b128 v[222:225], v174 offset:55296
	ds_read_b128 v[226:229], v174 offset:56320
	global_load_lds_dwordx4 v158, s[98:99]
	s_add_i32 m0, s34, 0x2000
	s_add_u32 s30, s30, 0x40080
	s_addc_u32 s31, s31, 0
	s_add_i32 s34, s54, s36
	global_load_lds_dwordx4 v144, s[98:99]
	s_mov_b32 m0, s34
	s_nop 0
	global_load_lds_dwordx4 v158, s[30:31]
	s_add_i32 m0, s34, 0x2000
	s_nop 0
	global_load_lds_dwordx4 v144, s[30:31]
	s_mov_b32 m0, s43
	s_nop 0
	global_load_lds_dwordx4 v148, s[100:101]
	s_mov_b32 m0, s44
	s_nop 0
	global_load_lds_dwordx4 v146, s[100:101]
	s_waitcnt vmcnt(8)
	s_waitcnt lgkmcnt(0)
	s_barrier
	s_waitcnt lgkmcnt(0)
	v_mfma_f32_16x16x32_bf16 v[108:111], v[128:131], v[184:187], v[108:111]
	v_mfma_f32_16x16x32_bf16 v[76:79], v[136:139], v[184:187], v[76:79]
	v_mfma_f32_16x16x32_bf16 v[104:107], v[128:131], v[192:195], v[104:107]
	v_mfma_f32_16x16x32_bf16 v[72:75], v[136:139], v[192:195], v[72:75]
	v_mfma_f32_16x16x32_bf16 v[100:103], v[128:131], v[200:203], v[100:103]
	v_mfma_f32_16x16x32_bf16 v[68:71], v[136:139], v[200:203], v[68:71]
	v_mfma_f32_16x16x32_bf16 v[96:99], v[128:131], v[222:225], v[96:99]
	v_mfma_f32_16x16x32_bf16 v[64:67], v[136:139], v[222:225], v[64:67]
	v_mfma_f32_16x16x32_bf16 v[108:111], v[132:135], v[188:191], v[108:111]
	v_mfma_f32_16x16x32_bf16 v[76:79], v[140:143], v[188:191], v[76:79]
	v_mfma_f32_16x16x32_bf16 v[104:107], v[132:135], v[196:199], v[104:107]
	v_mfma_f32_16x16x32_bf16 v[72:75], v[140:143], v[196:199], v[72:75]
	v_mfma_f32_16x16x32_bf16 v[100:103], v[132:135], v[218:221], v[100:103]
	v_mfma_f32_16x16x32_bf16 v[68:71], v[140:143], v[218:221], v[68:71]
	v_mfma_f32_16x16x32_bf16 v[96:99], v[132:135], v[226:229], v[96:99]
	v_mfma_f32_16x16x32_bf16 v[64:67], v[140:143], v[226:229], v[64:67]
	v_mfma_f32_16x16x32_bf16 v[44:47], v[164:167], v[184:187], v[44:47]
	v_mfma_f32_16x16x32_bf16 v[12:15], v[176:179], v[184:187], v[12:15]
	v_mfma_f32_16x16x32_bf16 v[40:43], v[164:167], v[192:195], v[40:43]
	v_mfma_f32_16x16x32_bf16 v[8:11], v[176:179], v[192:195], v[8:11]
	v_mfma_f32_16x16x32_bf16 v[36:39], v[164:167], v[200:203], v[36:39]
	v_mfma_f32_16x16x32_bf16 v[4:7], v[176:179], v[200:203], v[4:7]
	v_mfma_f32_16x16x32_bf16 v[32:35], v[164:167], v[222:225], v[32:35]
	v_mfma_f32_16x16x32_bf16 v[0:3], v[176:179], v[222:225], v[0:3]
	v_mfma_f32_16x16x32_bf16 v[44:47], v[168:171], v[188:191], v[44:47]
	v_mfma_f32_16x16x32_bf16 v[12:15], v[180:183], v[188:191], v[12:15]
	v_mfma_f32_16x16x32_bf16 v[40:43], v[168:171], v[196:199], v[40:43]
	v_mfma_f32_16x16x32_bf16 v[8:11], v[180:183], v[196:199], v[8:11]
	v_mfma_f32_16x16x32_bf16 v[36:39], v[168:171], v[218:221], v[36:39]
	v_mfma_f32_16x16x32_bf16 v[4:7], v[180:183], v[218:221], v[4:7]
	v_mfma_f32_16x16x32_bf16 v[32:35], v[168:171], v[226:229], v[32:35]
	v_mfma_f32_16x16x32_bf16 v[0:3], v[180:183], v[226:229], v[0:3]
	s_barrier
	s_add_i32 s52, s52, 2
	s_add_u32 s26, s26, 0x100
	s_addc_u32 s27, s27, 0
	s_add_u32 s50, s50, 0x100
	s_addc_u32 s51, s51, 0
	s_cmp_gt_u32 s52, 13
	s_cbranch_scc0 .LBB0_764
	s_and_b64 vcc, exec, s[16:17]
	s_mov_b32 s49, s57
	s_cbranch_vccz .LBB0_767
	s_barrier

.Lz_skip_4:
	s_waitcnt vmcnt(8)
	s_waitcnt lgkmcnt(0)
	s_barrier
	s_waitcnt lgkmcnt(0)
	v_mfma_f32_16x16x32_bf16 v[124:127], v[138:141], v[180:183], v[124:127]
	v_mfma_f32_16x16x32_bf16 v[120:123], v[154:157], v[180:183], v[120:123]
	v_mfma_f32_16x16x32_bf16 v[108:111], v[138:141], v[188:191], v[108:111]
	v_mfma_f32_16x16x32_bf16 v[104:107], v[154:157], v[188:191], v[104:107]
	v_mfma_f32_16x16x32_bf16 v[92:95], v[138:141], v[196:199], v[92:95]
	v_mfma_f32_16x16x32_bf16 v[88:91], v[154:157], v[196:199], v[88:91]
	v_mfma_f32_16x16x32_bf16 v[76:79], v[138:141], v[212:215], v[76:79]
	v_mfma_f32_16x16x32_bf16 v[72:75], v[154:157], v[212:215], v[72:75]
	v_mfma_f32_16x16x32_bf16 v[124:127], v[142:145], v[184:187], v[124:127]
	v_mfma_f32_16x16x32_bf16 v[120:123], v[160:163], v[184:187], v[120:123]
	v_mfma_f32_16x16x32_bf16 v[108:111], v[142:145], v[192:195], v[108:111]
	v_mfma_f32_16x16x32_bf16 v[104:107], v[160:163], v[192:195], v[104:107]
	v_mfma_f32_16x16x32_bf16 v[92:95], v[142:145], v[200:203], v[92:95]
	v_mfma_f32_16x16x32_bf16 v[88:91], v[160:163], v[200:203], v[88:91]
	v_mfma_f32_16x16x32_bf16 v[76:79], v[142:145], v[220:223], v[76:79]
	v_mfma_f32_16x16x32_bf16 v[72:75], v[160:163], v[220:223], v[72:75]
	v_mfma_f32_16x16x32_bf16 v[116:119], v[164:167], v[180:183], v[116:119]
	v_mfma_f32_16x16x32_bf16 v[112:115], v[172:175], v[180:183], v[112:115]
	v_mfma_f32_16x16x32_bf16 v[100:103], v[164:167], v[188:191], v[100:103]
	v_mfma_f32_16x16x32_bf16 v[96:99], v[172:175], v[188:191], v[96:99]
	v_mfma_f32_16x16x32_bf16 v[84:87], v[164:167], v[196:199], v[84:87]
	v_mfma_f32_16x16x32_bf16 v[80:83], v[172:175], v[196:199], v[80:83]
	v_mfma_f32_16x16x32_bf16 v[68:71], v[164:167], v[212:215], v[68:71]
	v_mfma_f32_16x16x32_bf16 v[64:67], v[172:175], v[212:215], v[64:67]
	v_mfma_f32_16x16x32_bf16 v[116:119], v[168:171], v[184:187], v[116:119]
	v_mfma_f32_16x16x32_bf16 v[112:115], v[176:179], v[184:187], v[112:115]
	v_mfma_f32_16x16x32_bf16 v[100:103], v[168:171], v[192:195], v[100:103]
	v_mfma_f32_16x16x32_bf16 v[96:99], v[176:179], v[192:195], v[96:99]
	v_mfma_f32_16x16x32_bf16 v[84:87], v[168:171], v[200:203], v[84:87]
	v_mfma_f32_16x16x32_bf16 v[80:83], v[176:179], v[200:203], v[80:83]
	v_mfma_f32_16x16x32_bf16 v[68:71], v[168:171], v[220:223], v[68:71]
	v_mfma_f32_16x16x32_bf16 v[64:67], v[176:179], v[220:223], v[64:67]
	s_barrier
	s_add_i32 s54, s54, s37
	s_add_u32 s98, s22, s28
	s_addc_u32 s99, s23, s29
	s_mov_b32 m0, s54
	ds_read_b128 v[180:183], v159 offset:16384
	ds_read_b128 v[184:187], v159 offset:17408
	ds_read_b128 v[188:191], v159 offset:18432
	ds_read_b128 v[192:195], v159 offset:19456
	ds_read_b128 v[196:199], v159 offset:20480
	ds_read_b128 v[200:203], v159 offset:21504
	ds_read_b128 v[212:215], v159 offset:22528
	ds_read_b128 v[220:223], v159 offset:23552
	global_load_lds_dwordx4 v148, s[22:23]
	s_add_i32 m0, s54, 0x2000
	s_add_u32 s54, s22, 0x20000
	s_addc_u32 s55, s23, 0
	s_add_i32 s56, s56, s37
	global_load_lds_dwordx4 v128, s[22:23]
	s_mov_b32 m0, s56
	s_add_u32 s100, s24, s28
	s_addc_u32 s101, s25, s29
	global_load_lds_dwordx4 v148, s[54:55]
	s_add_i32 m0, s56, 0x2000
	s_nop 0
	global_load_lds_dwordx4 v128, s[54:55]
	s_mov_b32 m0, s38
	s_nop 0
	global_load_lds_dwordx4 v132, s[24:25]
	s_mov_b32 m0, s39
	s_nop 0
	global_load_lds_dwordx4 v130, s[24:25]
	s_waitcnt vmcnt(8)
	s_waitcnt lgkmcnt(0)
	s_barrier
	s_waitcnt lgkmcnt(0)
	v_mfma_f32_16x16x32_bf16 v[60:63], v[138:141], v[180:183], v[60:63]
	v_mfma_f32_16x16x32_bf16 v[56:59], v[154:157], v[180:183], v[56:59]
	v_mfma_f32_16x16x32_bf16 v[44:47], v[138:141], v[188:191], v[44:47]
	v_mfma_f32_16x16x32_bf16 v[40:43], v[154:157], v[188:191], v[40:43]
	v_mfma_f32_16x16x32_bf16 v[28:31], v[138:141], v[196:199], v[28:31]
	v_mfma_f32_16x16x32_bf16 v[24:27], v[154:157], v[196:199], v[24:27]
	v_mfma_f32_16x16x32_bf16 v[12:15], v[138:141], v[212:215], v[12:15]
	v_mfma_f32_16x16x32_bf16 v[8:11], v[154:157], v[212:215], v[8:11]
	v_mfma_f32_16x16x32_bf16 v[60:63], v[142:145], v[184:187], v[60:63]
	v_mfma_f32_16x16x32_bf16 v[56:59], v[160:163], v[184:187], v[56:59]
	v_mfma_f32_16x16x32_bf16 v[44:47], v[142:145], v[192:195], v[44:47]
	v_mfma_f32_16x16x32_bf16 v[40:43], v[160:163], v[192:195], v[40:43]
	v_mfma_f32_16x16x32_bf16 v[28:31], v[142:145], v[200:203], v[28:31]
	v_mfma_f32_16x16x32_bf16 v[24:27], v[160:163], v[200:203], v[24:27]
	v_mfma_f32_16x16x32_bf16 v[12:15], v[142:145], v[220:223], v[12:15]
	v_mfma_f32_16x16x32_bf16 v[8:11], v[160:163], v[220:223], v[8:11]
	v_mfma_f32_16x16x32_bf16 v[52:55], v[164:167], v[180:183], v[52:55]
	v_mfma_f32_16x16x32_bf16 v[48:51], v[172:175], v[180:183], v[48:51]
	v_mfma_f32_16x16x32_bf16 v[36:39], v[164:167], v[188:191], v[36:39]
	v_mfma_f32_16x16x32_bf16 v[32:35], v[172:175], v[188:191], v[32:35]
	v_mfma_f32_16x16x32_bf16 v[20:23], v[164:167], v[196:199], v[20:23]
	v_mfma_f32_16x16x32_bf16 v[16:19], v[172:175], v[196:199], v[16:19]
	v_mfma_f32_16x16x32_bf16 v[4:7], v[164:167], v[212:215], v[4:7]
	v_mfma_f32_16x16x32_bf16 v[0:3], v[172:175], v[212:215], v[0:3]
	v_mfma_f32_16x16x32_bf16 v[52:55], v[168:171], v[184:187], v[52:55]
	v_mfma_f32_16x16x32_bf16 v[48:51], v[176:179], v[184:187], v[48:51]
	v_mfma_f32_16x16x32_bf16 v[36:39], v[168:171], v[192:195], v[36:39]
	v_mfma_f32_16x16x32_bf16 v[32:35], v[176:179], v[192:195], v[32:35]
	v_mfma_f32_16x16x32_bf16 v[20:23], v[168:171], v[200:203], v[20:23]
	v_mfma_f32_16x16x32_bf16 v[16:19], v[176:179], v[200:203], v[16:19]
	v_mfma_f32_16x16x32_bf16 v[4:7], v[168:171], v[220:223], v[4:7]
	v_mfma_f32_16x16x32_bf16 v[0:3], v[176:179], v[220:223], v[0:3]
	s_barrier
	s_add_i32 s54, 0, 0x18000
	s_add_i32 s55, 0, 0x1c000
	v_add_u32_e32 v160, s54, v158
	v_add_u32_e32 v176, s55, v158
	ds_read_b128 v[138:141], v160
	ds_read_b128 v[142:145], v160 offset:1024
	ds_read_b128 v[154:157], v160 offset:2048
	ds_read_b128 v[160:163], v160 offset:3072
	ds_read_b128 v[164:167], v176
	ds_read_b128 v[168:171], v176 offset:1024
	ds_read_b128 v[172:175], v176 offset:2048
	ds_read_b128 v[176:179], v176 offset:3072
	s_add_u32 s24, s24, 0x20000
	s_addc_u32 s25, s25, 0
	s_mov_b32 m0, s40
	ds_read_b128 v[180:183], v159 offset:32768
	ds_read_b128 v[184:187], v159 offset:33792
	ds_read_b128 v[188:191], v159 offset:34816
	ds_read_b128 v[192:195], v159 offset:35840
	ds_read_b128 v[196:199], v159 offset:36864
	ds_read_b128 v[200:203], v159 offset:37888
	ds_read_b128 v[212:215], v159 offset:38912
	ds_read_b128 v[220:223], v159 offset:39936
	global_load_lds_dwordx4 v132, s[24:25]
	s_mov_b32 m0, s41
	s_nop 0
	global_load_lds_dwordx4 v130, s[24:25]
	s_waitcnt vmcnt(8)
	s_waitcnt lgkmcnt(0)
	s_barrier
	s_waitcnt lgkmcnt(0)
	v_mfma_f32_16x16x32_bf16 v[124:127], v[138:141], v[180:183], v[124:127]
	v_mfma_f32_16x16x32_bf16 v[120:123], v[154:157], v[180:183], v[120:123]
	v_mfma_f32_16x16x32_bf16 v[108:111], v[138:141], v[188:191], v[108:111]
	v_mfma_f32_16x16x32_bf16 v[104:107], v[154:157], v[188:191], v[104:107]
	v_mfma_f32_16x16x32_bf16 v[92:95], v[138:141], v[196:199], v[92:95]
	v_mfma_f32_16x16x32_bf16 v[88:91], v[154:157], v[196:199], v[88:91]
	v_mfma_f32_16x16x32_bf16 v[76:79], v[138:141], v[212:215], v[76:79]
	v_mfma_f32_16x16x32_bf16 v[72:75], v[154:157], v[212:215], v[72:75]
	v_mfma_f32_16x16x32_bf16 v[124:127], v[142:145], v[184:187], v[124:127]
	v_mfma_f32_16x16x32_bf16 v[120:123], v[160:163], v[184:187], v[120:123]
	v_mfma_f32_16x16x32_bf16 v[108:111], v[142:145], v[192:195], v[108:111]
	v_mfma_f32_16x16x32_bf16 v[104:107], v[160:163], v[192:195], v[104:107]
	v_mfma_f32_16x16x32_bf16 v[92:95], v[142:145], v[200:203], v[92:95]
	v_mfma_f32_16x16x32_bf16 v[88:91], v[160:163], v[200:203], v[88:91]
	v_mfma_f32_16x16x32_bf16 v[76:79], v[142:145], v[220:223], v[76:79]
	v_mfma_f32_16x16x32_bf16 v[72:75], v[160:163], v[220:223], v[72:75]
	v_mfma_f32_16x16x32_bf16 v[116:119], v[164:167], v[180:183], v[116:119]
	v_mfma_f32_16x16x32_bf16 v[112:115], v[172:175], v[180:183], v[112:115]
	v_mfma_f32_16x16x32_bf16 v[100:103], v[164:167], v[188:191], v[100:103]
	v_mfma_f32_16x16x32_bf16 v[96:99], v[172:175], v[188:191], v[96:99]
	v_mfma_f32_16x16x32_bf16 v[84:87], v[164:167], v[196:199], v[84:87]
	v_mfma_f32_16x16x32_bf16 v[80:83], v[172:175], v[196:199], v[80:83]
	v_mfma_f32_16x16x32_bf16 v[68:71], v[164:167], v[212:215], v[68:71]
	v_mfma_f32_16x16x32_bf16 v[64:67], v[172:175], v[212:215], v[64:67]
	v_mfma_f32_16x16x32_bf16 v[116:119], v[168:171], v[184:187], v[116:119]
	v_mfma_f32_16x16x32_bf16 v[112:115], v[176:179], v[184:187], v[112:115]
	v_mfma_f32_16x16x32_bf16 v[100:103], v[168:171], v[192:195], v[100:103]
	v_mfma_f32_16x16x32_bf16 v[96:99], v[176:179], v[192:195], v[96:99]
	v_mfma_f32_16x16x32_bf16 v[84:87], v[168:171], v[200:203], v[84:87]
	v_mfma_f32_16x16x32_bf16 v[80:83], v[176:179], v[200:203], v[80:83]
	v_mfma_f32_16x16x32_bf16 v[68:71], v[168:171], v[220:223], v[68:71]
	v_mfma_f32_16x16x32_bf16 v[64:67], v[176:179], v[220:223], v[64:67]
	s_barrier
	s_add_i32 s24, s54, s37
	s_mov_b32 m0, s24
	ds_read_b128 v[180:183], v159 offset:49152
	ds_read_b128 v[184:187], v159 offset:50176
	ds_read_b128 v[188:191], v159 offset:51200
	ds_read_b128 v[192:195], v159 offset:52224
	ds_read_b128 v[196:199], v159 offset:53248
	ds_read_b128 v[200:203], v159 offset:54272
	ds_read_b128 v[212:215], v159 offset:55296
	ds_read_b128 v[220:223], v159 offset:56320
	global_load_lds_dwordx4 v148, s[98:99]
	s_add_i32 m0, s24, 0x2000
	s_add_u32 s22, s22, 0x20080
	s_addc_u32 s23, s23, 0
	s_add_i32 s24, s55, s37
	global_load_lds_dwordx4 v128, s[98:99]
	s_mov_b32 m0, s24
	s_nop 0
	global_load_lds_dwordx4 v148, s[22:23]
	s_add_i32 m0, s24, 0x2000
	s_nop 0
	global_load_lds_dwordx4 v128, s[22:23]
	s_mov_b32 m0, s45
	s_nop 0
	global_load_lds_dwordx4 v132, s[100:101]
	s_mov_b32 m0, s46
	s_nop 0
	global_load_lds_dwordx4 v130, s[100:101]
	s_waitcnt vmcnt(8)
	s_waitcnt lgkmcnt(0)
	s_barrier
	s_waitcnt lgkmcnt(0)
	v_mfma_f32_16x16x32_bf16 v[60:63], v[138:141], v[180:183], v[60:63]
	v_mfma_f32_16x16x32_bf16 v[56:59], v[154:157], v[180:183], v[56:59]
	v_mfma_f32_16x16x32_bf16 v[44:47], v[138:141], v[188:191], v[44:47]
	v_mfma_f32_16x16x32_bf16 v[40:43], v[154:157], v[188:191], v[40:43]
	v_mfma_f32_16x16x32_bf16 v[28:31], v[138:141], v[196:199], v[28:31]
	v_mfma_f32_16x16x32_bf16 v[24:27], v[154:157], v[196:199], v[24:27]
	v_mfma_f32_16x16x32_bf16 v[12:15], v[138:141], v[212:215], v[12:15]
	v_mfma_f32_16x16x32_bf16 v[8:11], v[154:157], v[212:215], v[8:11]
	v_mfma_f32_16x16x32_bf16 v[60:63], v[142:145], v[184:187], v[60:63]
	v_mfma_f32_16x16x32_bf16 v[56:59], v[160:163], v[184:187], v[56:59]
	v_mfma_f32_16x16x32_bf16 v[44:47], v[142:145], v[192:195], v[44:47]
	v_mfma_f32_16x16x32_bf16 v[40:43], v[160:163], v[192:195], v[40:43]
	v_mfma_f32_16x16x32_bf16 v[28:31], v[142:145], v[200:203], v[28:31]
	v_mfma_f32_16x16x32_bf16 v[24:27], v[160:163], v[200:203], v[24:27]
	v_mfma_f32_16x16x32_bf16 v[12:15], v[142:145], v[220:223], v[12:15]
	v_mfma_f32_16x16x32_bf16 v[8:11], v[160:163], v[220:223], v[8:11]
	v_mfma_f32_16x16x32_bf16 v[52:55], v[164:167], v[180:183], v[52:55]
	v_mfma_f32_16x16x32_bf16 v[48:51], v[172:175], v[180:183], v[48:51]
	v_mfma_f32_16x16x32_bf16 v[36:39], v[164:167], v[188:191], v[36:39]
	v_mfma_f32_16x16x32_bf16 v[32:35], v[172:175], v[188:191], v[32:35]
	v_mfma_f32_16x16x32_bf16 v[20:23], v[164:167], v[196:199], v[20:23]
	v_mfma_f32_16x16x32_bf16 v[16:19], v[172:175], v[196:199], v[16:19]
	v_mfma_f32_16x16x32_bf16 v[4:7], v[164:167], v[212:215], v[4:7]
	v_mfma_f32_16x16x32_bf16 v[0:3], v[172:175], v[212:215], v[0:3]
	v_mfma_f32_16x16x32_bf16 v[52:55], v[168:171], v[184:187], v[52:55]
	v_mfma_f32_16x16x32_bf16 v[48:51], v[176:179], v[184:187], v[48:51]
	v_mfma_f32_16x16x32_bf16 v[36:39], v[168:171], v[192:195], v[36:39]
	v_mfma_f32_16x16x32_bf16 v[32:35], v[176:179], v[192:195], v[32:35]
	v_mfma_f32_16x16x32_bf16 v[20:23], v[168:171], v[200:203], v[20:23]
	v_mfma_f32_16x16x32_bf16 v[16:19], v[176:179], v[200:203], v[16:19]
	v_mfma_f32_16x16x32_bf16 v[4:7], v[168:171], v[220:223], v[4:7]
	v_mfma_f32_16x16x32_bf16 v[0:3], v[176:179], v[220:223], v[0:3]
	s_barrier
	s_add_i32 s53, s53, 2
	s_add_u32 s8, s8, 0x100
	s_addc_u32 s9, s9, 0
	s_add_u32 s51, s51, 0x100
	s_addc_u32 s52, s52, 0
	s_cmp_gt_u32 s53, 5
	s_cbranch_scc0 .LBB0_1335
	s_and_b64 vcc, exec, s[12:13]
	s_cbranch_vccz .LBB0_1338
	s_barrier

.Lz_skip_5:
	s_waitcnt vmcnt(8)
	s_waitcnt lgkmcnt(0)
	s_barrier
	s_waitcnt lgkmcnt(0)
	v_mfma_f32_16x16x32_bf16 v[124:127], v[138:141], v[182:185], v[124:127]
	v_mfma_f32_16x16x32_bf16 v[120:123], v[158:161], v[182:185], v[120:123]
	v_mfma_f32_16x16x32_bf16 v[108:111], v[138:141], v[190:193], v[108:111]
	v_mfma_f32_16x16x32_bf16 v[104:107], v[158:161], v[190:193], v[104:107]
	v_mfma_f32_16x16x32_bf16 v[92:95], v[138:141], v[198:201], v[92:95]
	v_mfma_f32_16x16x32_bf16 v[88:91], v[158:161], v[198:201], v[88:91]
	v_mfma_f32_16x16x32_bf16 v[76:79], v[138:141], v[212:215], v[76:79]
	v_mfma_f32_16x16x32_bf16 v[72:75], v[158:161], v[212:215], v[72:75]
	v_mfma_f32_16x16x32_bf16 v[124:127], v[154:157], v[186:189], v[124:127]
	v_mfma_f32_16x16x32_bf16 v[120:123], v[162:165], v[186:189], v[120:123]
	v_mfma_f32_16x16x32_bf16 v[108:111], v[154:157], v[194:197], v[108:111]
	v_mfma_f32_16x16x32_bf16 v[104:107], v[162:165], v[194:197], v[104:107]
	v_mfma_f32_16x16x32_bf16 v[92:95], v[154:157], v[202:205], v[92:95]
	v_mfma_f32_16x16x32_bf16 v[88:91], v[162:165], v[202:205], v[88:91]
	v_mfma_f32_16x16x32_bf16 v[76:79], v[154:157], v[220:223], v[76:79]
	v_mfma_f32_16x16x32_bf16 v[72:75], v[162:165], v[220:223], v[72:75]
	v_mfma_f32_16x16x32_bf16 v[116:119], v[166:169], v[182:185], v[116:119]
	v_mfma_f32_16x16x32_bf16 v[112:115], v[174:177], v[182:185], v[112:115]
	v_mfma_f32_16x16x32_bf16 v[100:103], v[166:169], v[190:193], v[100:103]
	v_mfma_f32_16x16x32_bf16 v[96:99], v[174:177], v[190:193], v[96:99]
	v_mfma_f32_16x16x32_bf16 v[84:87], v[166:169], v[198:201], v[84:87]
	v_mfma_f32_16x16x32_bf16 v[80:83], v[174:177], v[198:201], v[80:83]
	v_mfma_f32_16x16x32_bf16 v[68:71], v[166:169], v[212:215], v[68:71]
	v_mfma_f32_16x16x32_bf16 v[64:67], v[174:177], v[212:215], v[64:67]
	v_mfma_f32_16x16x32_bf16 v[116:119], v[170:173], v[186:189], v[116:119]
	v_mfma_f32_16x16x32_bf16 v[112:115], v[178:181], v[186:189], v[112:115]
	v_mfma_f32_16x16x32_bf16 v[100:103], v[170:173], v[194:197], v[100:103]
	v_mfma_f32_16x16x32_bf16 v[96:99], v[178:181], v[194:197], v[96:99]
	v_mfma_f32_16x16x32_bf16 v[84:87], v[170:173], v[202:205], v[84:87]
	v_mfma_f32_16x16x32_bf16 v[80:83], v[178:181], v[202:205], v[80:83]
	v_mfma_f32_16x16x32_bf16 v[68:71], v[170:173], v[220:223], v[68:71]
	v_mfma_f32_16x16x32_bf16 v[64:67], v[178:181], v[220:223], v[64:67]
	s_barrier
	s_add_i32 s49, s49, s30
	s_add_u32 s98, s20, s28
	s_addc_u32 s99, s21, s29
	s_mov_b32 m0, s49
	ds_read_b128 v[182:185], v145 offset:16384
	ds_read_b128 v[186:189], v145 offset:17408
	ds_read_b128 v[190:193], v145 offset:18432
	ds_read_b128 v[194:197], v145 offset:19456
	ds_read_b128 v[198:201], v145 offset:20480
	ds_read_b128 v[202:205], v145 offset:21504
	ds_read_b128 v[212:215], v145 offset:22528
	ds_read_b128 v[220:223], v145 offset:23552
	global_load_lds_dwordx4 v148, s[20:21]
	s_add_i32 m0, s49, 0x2000
	s_add_u32 s50, s20, 0x40000
	s_addc_u32 s51, s21, 0
	s_add_i32 s49, s52, s30
	global_load_lds_dwordx4 v128, s[20:21]
	s_mov_b32 m0, s49
	s_add_u32 s100, s22, s28
	s_addc_u32 s101, s23, s29
	global_load_lds_dwordx4 v148, s[50:51]
	s_add_i32 m0, s49, 0x2000
	s_nop 0
	global_load_lds_dwordx4 v128, s[50:51]
	s_mov_b32 m0, s31
	s_nop 0
	global_load_lds_dwordx4 v132, s[22:23]
	s_mov_b32 m0, s33
	s_nop 0
	global_load_lds_dwordx4 v130, s[22:23]
	s_waitcnt vmcnt(8)
	s_waitcnt lgkmcnt(0)
	s_barrier
	s_waitcnt lgkmcnt(0)
	v_mfma_f32_16x16x32_bf16 v[60:63], v[138:141], v[182:185], v[60:63]
	v_mfma_f32_16x16x32_bf16 v[56:59], v[158:161], v[182:185], v[56:59]
	v_mfma_f32_16x16x32_bf16 v[44:47], v[138:141], v[190:193], v[44:47]
	v_mfma_f32_16x16x32_bf16 v[40:43], v[158:161], v[190:193], v[40:43]
	v_mfma_f32_16x16x32_bf16 v[28:31], v[138:141], v[198:201], v[28:31]
	v_mfma_f32_16x16x32_bf16 v[24:27], v[158:161], v[198:201], v[24:27]
	v_mfma_f32_16x16x32_bf16 v[12:15], v[138:141], v[212:215], v[12:15]
	v_mfma_f32_16x16x32_bf16 v[8:11], v[158:161], v[212:215], v[8:11]
	v_mfma_f32_16x16x32_bf16 v[60:63], v[154:157], v[186:189], v[60:63]
	v_mfma_f32_16x16x32_bf16 v[56:59], v[162:165], v[186:189], v[56:59]
	v_mfma_f32_16x16x32_bf16 v[44:47], v[154:157], v[194:197], v[44:47]
	v_mfma_f32_16x16x32_bf16 v[40:43], v[162:165], v[194:197], v[40:43]
	v_mfma_f32_16x16x32_bf16 v[28:31], v[154:157], v[202:205], v[28:31]
	v_mfma_f32_16x16x32_bf16 v[24:27], v[162:165], v[202:205], v[24:27]
	v_mfma_f32_16x16x32_bf16 v[12:15], v[154:157], v[220:223], v[12:15]
	v_mfma_f32_16x16x32_bf16 v[8:11], v[162:165], v[220:223], v[8:11]
	v_mfma_f32_16x16x32_bf16 v[52:55], v[166:169], v[182:185], v[52:55]
	v_mfma_f32_16x16x32_bf16 v[48:51], v[174:177], v[182:185], v[48:51]
	v_mfma_f32_16x16x32_bf16 v[36:39], v[166:169], v[190:193], v[36:39]
	v_mfma_f32_16x16x32_bf16 v[32:35], v[174:177], v[190:193], v[32:35]
	v_mfma_f32_16x16x32_bf16 v[20:23], v[166:169], v[198:201], v[20:23]
	v_mfma_f32_16x16x32_bf16 v[16:19], v[174:177], v[198:201], v[16:19]
	v_mfma_f32_16x16x32_bf16 v[4:7], v[166:169], v[212:215], v[4:7]
	v_mfma_f32_16x16x32_bf16 v[0:3], v[174:177], v[212:215], v[0:3]
	v_mfma_f32_16x16x32_bf16 v[52:55], v[170:173], v[186:189], v[52:55]
	v_mfma_f32_16x16x32_bf16 v[48:51], v[178:181], v[186:189], v[48:51]
	v_mfma_f32_16x16x32_bf16 v[36:39], v[170:173], v[194:197], v[36:39]
	v_mfma_f32_16x16x32_bf16 v[32:35], v[178:181], v[194:197], v[32:35]
	v_mfma_f32_16x16x32_bf16 v[20:23], v[170:173], v[202:205], v[20:23]
	v_mfma_f32_16x16x32_bf16 v[16:19], v[178:181], v[202:205], v[16:19]
	v_mfma_f32_16x16x32_bf16 v[4:7], v[170:173], v[220:223], v[4:7]
	v_mfma_f32_16x16x32_bf16 v[0:3], v[178:181], v[220:223], v[0:3]
	s_barrier
	s_add_i32 s49, 0, 0x18000
	s_add_i32 s50, 0, 0x1c000
	v_add_u32_e32 v162, s49, v144
	v_add_u32_e32 v178, s50, v144
	ds_read_b128 v[138:141], v162
	ds_read_b128 v[154:157], v162 offset:1024
	ds_read_b128 v[158:161], v162 offset:2048
	ds_read_b128 v[162:165], v162 offset:3072
	ds_read_b128 v[166:169], v178
	ds_read_b128 v[170:173], v178 offset:1024
	ds_read_b128 v[174:177], v178 offset:2048
	ds_read_b128 v[178:181], v178 offset:3072
	s_add_u32 s22, s22, 0x40000
	s_addc_u32 s23, s23, 0
	s_mov_b32 m0, s34
	ds_read_b128 v[182:185], v145 offset:32768
	ds_read_b128 v[186:189], v145 offset:33792
	ds_read_b128 v[190:193], v145 offset:34816
	ds_read_b128 v[194:197], v145 offset:35840
	ds_read_b128 v[198:201], v145 offset:36864
	ds_read_b128 v[202:205], v145 offset:37888
	ds_read_b128 v[212:215], v145 offset:38912
	ds_read_b128 v[220:223], v145 offset:39936
	global_load_lds_dwordx4 v132, s[22:23]
	s_mov_b32 m0, s35
	s_nop 0
	global_load_lds_dwordx4 v130, s[22:23]
	s_waitcnt vmcnt(8)
	s_waitcnt lgkmcnt(0)
	s_barrier
	s_waitcnt lgkmcnt(0)
	v_mfma_f32_16x16x32_bf16 v[124:127], v[138:141], v[182:185], v[124:127]
	v_mfma_f32_16x16x32_bf16 v[120:123], v[158:161], v[182:185], v[120:123]
	v_mfma_f32_16x16x32_bf16 v[108:111], v[138:141], v[190:193], v[108:111]
	v_mfma_f32_16x16x32_bf16 v[104:107], v[158:161], v[190:193], v[104:107]
	v_mfma_f32_16x16x32_bf16 v[92:95], v[138:141], v[198:201], v[92:95]
	v_mfma_f32_16x16x32_bf16 v[88:91], v[158:161], v[198:201], v[88:91]
	v_mfma_f32_16x16x32_bf16 v[76:79], v[138:141], v[212:215], v[76:79]
	v_mfma_f32_16x16x32_bf16 v[72:75], v[158:161], v[212:215], v[72:75]
	v_mfma_f32_16x16x32_bf16 v[124:127], v[154:157], v[186:189], v[124:127]
	v_mfma_f32_16x16x32_bf16 v[120:123], v[162:165], v[186:189], v[120:123]
	v_mfma_f32_16x16x32_bf16 v[108:111], v[154:157], v[194:197], v[108:111]
	v_mfma_f32_16x16x32_bf16 v[104:107], v[162:165], v[194:197], v[104:107]
	v_mfma_f32_16x16x32_bf16 v[92:95], v[154:157], v[202:205], v[92:95]
	v_mfma_f32_16x16x32_bf16 v[88:91], v[162:165], v[202:205], v[88:91]
	v_mfma_f32_16x16x32_bf16 v[76:79], v[154:157], v[220:223], v[76:79]
	v_mfma_f32_16x16x32_bf16 v[72:75], v[162:165], v[220:223], v[72:75]
	v_mfma_f32_16x16x32_bf16 v[116:119], v[166:169], v[182:185], v[116:119]
	v_mfma_f32_16x16x32_bf16 v[112:115], v[174:177], v[182:185], v[112:115]
	v_mfma_f32_16x16x32_bf16 v[100:103], v[166:169], v[190:193], v[100:103]
	v_mfma_f32_16x16x32_bf16 v[96:99], v[174:177], v[190:193], v[96:99]
	v_mfma_f32_16x16x32_bf16 v[84:87], v[166:169], v[198:201], v[84:87]
	v_mfma_f32_16x16x32_bf16 v[80:83], v[174:177], v[198:201], v[80:83]
	v_mfma_f32_16x16x32_bf16 v[68:71], v[166:169], v[212:215], v[68:71]
	v_mfma_f32_16x16x32_bf16 v[64:67], v[174:177], v[212:215], v[64:67]
	v_mfma_f32_16x16x32_bf16 v[116:119], v[170:173], v[186:189], v[116:119]
	v_mfma_f32_16x16x32_bf16 v[112:115], v[178:181], v[186:189], v[112:115]
	v_mfma_f32_16x16x32_bf16 v[100:103], v[170:173], v[194:197], v[100:103]
	v_mfma_f32_16x16x32_bf16 v[96:99], v[178:181], v[194:197], v[96:99]
	v_mfma_f32_16x16x32_bf16 v[84:87], v[170:173], v[202:205], v[84:87]
	v_mfma_f32_16x16x32_bf16 v[80:83], v[178:181], v[202:205], v[80:83]
	v_mfma_f32_16x16x32_bf16 v[68:71], v[170:173], v[220:223], v[68:71]
	v_mfma_f32_16x16x32_bf16 v[64:67], v[178:181], v[220:223], v[64:67]
	s_barrier
	s_add_i32 s22, s49, s30
	s_mov_b32 m0, s22
	ds_read_b128 v[182:185], v145 offset:49152
	ds_read_b128 v[186:189], v145 offset:50176
	ds_read_b128 v[190:193], v145 offset:51200
	ds_read_b128 v[194:197], v145 offset:52224
	ds_read_b128 v[198:201], v145 offset:53248
	ds_read_b128 v[202:205], v145 offset:54272
	ds_read_b128 v[212:215], v145 offset:55296
	ds_read_b128 v[220:223], v145 offset:56320
	global_load_lds_dwordx4 v148, s[98:99]
	s_add_i32 m0, s22, 0x2000
	s_add_u32 s20, s20, 0x40080
	s_addc_u32 s21, s21, 0
	s_add_i32 s22, s50, s30
	global_load_lds_dwordx4 v128, s[98:99]
	s_mov_b32 m0, s22
	s_nop 0
	global_load_lds_dwordx4 v148, s[20:21]
	s_add_i32 m0, s22, 0x2000
	s_nop 0
	global_load_lds_dwordx4 v128, s[20:21]
	s_mov_b32 m0, s39
	s_nop 0
	global_load_lds_dwordx4 v132, s[100:101]
	s_mov_b32 m0, s40
	s_nop 0
	global_load_lds_dwordx4 v130, s[100:101]
	s_waitcnt vmcnt(8)
	s_waitcnt lgkmcnt(0)
	s_barrier
	s_waitcnt lgkmcnt(0)
	v_mfma_f32_16x16x32_bf16 v[60:63], v[138:141], v[182:185], v[60:63]
	v_mfma_f32_16x16x32_bf16 v[56:59], v[158:161], v[182:185], v[56:59]
	v_mfma_f32_16x16x32_bf16 v[44:47], v[138:141], v[190:193], v[44:47]
	v_mfma_f32_16x16x32_bf16 v[40:43], v[158:161], v[190:193], v[40:43]
	v_mfma_f32_16x16x32_bf16 v[28:31], v[138:141], v[198:201], v[28:31]
	v_mfma_f32_16x16x32_bf16 v[24:27], v[158:161], v[198:201], v[24:27]
	v_mfma_f32_16x16x32_bf16 v[12:15], v[138:141], v[212:215], v[12:15]
	v_mfma_f32_16x16x32_bf16 v[8:11], v[158:161], v[212:215], v[8:11]
	v_mfma_f32_16x16x32_bf16 v[60:63], v[154:157], v[186:189], v[60:63]
	v_mfma_f32_16x16x32_bf16 v[56:59], v[162:165], v[186:189], v[56:59]
	v_mfma_f32_16x16x32_bf16 v[44:47], v[154:157], v[194:197], v[44:47]
	v_mfma_f32_16x16x32_bf16 v[40:43], v[162:165], v[194:197], v[40:43]
	v_mfma_f32_16x16x32_bf16 v[28:31], v[154:157], v[202:205], v[28:31]
	v_mfma_f32_16x16x32_bf16 v[24:27], v[162:165], v[202:205], v[24:27]
	v_mfma_f32_16x16x32_bf16 v[12:15], v[154:157], v[220:223], v[12:15]
	v_mfma_f32_16x16x32_bf16 v[8:11], v[162:165], v[220:223], v[8:11]
	v_mfma_f32_16x16x32_bf16 v[52:55], v[166:169], v[182:185], v[52:55]
	v_mfma_f32_16x16x32_bf16 v[48:51], v[174:177], v[182:185], v[48:51]
	v_mfma_f32_16x16x32_bf16 v[36:39], v[166:169], v[190:193], v[36:39]
	v_mfma_f32_16x16x32_bf16 v[32:35], v[174:177], v[190:193], v[32:35]
	v_mfma_f32_16x16x32_bf16 v[20:23], v[166:169], v[198:201], v[20:23]
	v_mfma_f32_16x16x32_bf16 v[16:19], v[174:177], v[198:201], v[16:19]
	v_mfma_f32_16x16x32_bf16 v[4:7], v[166:169], v[212:215], v[4:7]
	v_mfma_f32_16x16x32_bf16 v[0:3], v[174:177], v[212:215], v[0:3]
	v_mfma_f32_16x16x32_bf16 v[52:55], v[170:173], v[186:189], v[52:55]
	v_mfma_f32_16x16x32_bf16 v[48:51], v[178:181], v[186:189], v[48:51]
	v_mfma_f32_16x16x32_bf16 v[36:39], v[170:173], v[194:197], v[36:39]
	v_mfma_f32_16x16x32_bf16 v[32:35], v[178:181], v[194:197], v[32:35]
	v_mfma_f32_16x16x32_bf16 v[20:23], v[170:173], v[202:205], v[20:23]
	v_mfma_f32_16x16x32_bf16 v[16:19], v[178:181], v[202:205], v[16:19]
	v_mfma_f32_16x16x32_bf16 v[4:7], v[170:173], v[220:223], v[4:7]
	v_mfma_f32_16x16x32_bf16 v[0:3], v[178:181], v[220:223], v[0:3]
	s_barrier
	s_add_i32 s48, s48, 2
	s_add_u32 s18, s18, 0x100
	s_addc_u32 s19, s19, 0
	s_add_u32 s46, s46, 0x100
	s_addc_u32 s47, s47, 0
	s_cmp_gt_u32 s48, 13
	s_cbranch_scc0 .LBB0_1438
	s_and_b64 vcc, exec, s[8:9]
	s_cbranch_vccz .LBB0_1441
	s_barrier
